# full-line LDS-DMA relayout on 7 GEMM instances (E1 x2, O1 x2, E3 x2, O3 L1) + coalesced epilogues (E1 x2, O3 L3)
# baseline (speedup 1.0000x reference)
; #define PG8_STAGE(bufoff, gbase, voff) do { _Pragma("unroll") for (int _i = 0; _i < 2; ++_i) \
;         __builtin_amdgcn_global_load_lds((const unsigned*)((const char*)(gbase) + (voff)[_i]), (LAS unsigned*)(lds + (bufoff) + ldsw + _i * 8192), 16, 0, 0); } while (0)
; #define PG8_WAIT_V(n) asm volatile("s_waitcnt vmcnt(" #n ")" ::: "memory")
; #define PG8_BAR __builtin_amdgcn_s_barrier()
; template <class Epi, class Sched>
; __device__ __forceinline__ void gemm_phase(LAS unsigned char* lds, const int K, const int lda, const int ldb, const Sched& S, const Epi& E) {
;     ...
;     for (int i = 0; i < 2; ++i) { int R, C; stage_rc(tid * 16 + i * 8192, R, C); const int Rb = (R & ~31) + perm32(R & 31);
;         voffA[i] = (unsigned)(R * lda + C) * 2u; voffB[i] = (unsigned)(Rb * ldb + C) * 2u; }
;     const size_t kstep = (size_t)(BK * 2);
;     const size_t hA = (size_t)HALF * lda * 2, hB = (size_t)HALF * ldb * 2;
;     const unsigned ldsw = (unsigned)wid * 1024u;
;     const int aoff = lds_byte(wr * 64 + fr, fq * 8), boff = lds_byte(wc * 32 + fr, fq * 8);
;     ...
;     const char* cA = S.aptr(cur); const char* cB = S.bptr(cur);
;     PG8_STAGE(PG8_SB(0, 0), cB, voffB); PG8_STAGE(PG8_SB(0, 1), cB + hB, voffB); PG8_STAGE(PG8_SA(0, 0), cA, voffA); PG8_STAGE(PG8_SA(0, 1), cA + hA, voffA);
;     if (wr == 1) PG8_BAR;
;     PG8_WAIT_V(2); PG8_BAR;
.LBB0_606:
	v_readlane_b32 s0, v255, 24
	v_readlane_b32 s1, v255, 25
	s_and_b64 vcc, exec, s[0:1]
	s_cbranch_vccnz .LBB0_644
	v_ashrrev_i32_e32 v1, 31, v8
	v_lshrrev_b32_e32 v1, 26, v1
	v_add_u32_e32 v1, v8, v1
	v_ashrrev_i32_e32 v9, 6, v1
	v_bfe_i32 v1, v8, 27, 1
	v_lshlrev_b32_e32 v0, 4, v8
	v_lshrrev_b32_e32 v1, 22, v1
	v_add_u32_e32 v1, v0, v1
	v_and_b32_e32 v1, 0xfffffc00, v1
	v_sub_u32_e32 v1, v0, v1
	v_lshrrev_b32_e32 v2, 4, v1
	v_bitop3_b32 v1, v2, v1, 32 bitop3:0x6c
	v_ashrrev_i32_e32 v3, 31, v1
	v_lshrrev_b32_e32 v3, 26, v3
	v_add_u32_e32 v3, v1, v3
	v_lshlrev_b32_e32 v2, 3, v9
	v_ashrrev_i32_e32 v10, 6, v3
	v_and_b32_e32 v3, 0xc0, v3
	v_and_b32_e32 v2, -16, v2
	v_sub_u32_e32 v1, v1, v3
	v_mov_b32_e32 v3, 1
	v_add_u32_e32 v2, v10, v2
	v_ashrrev_i16_sdwa v1, v3, sext(v1) dst_sel:DWORD dst_unused:UNUSED_PAD src0_sel:DWORD src1_sel:BYTE_0
	v_lshlrev_b32_e32 v4, 5, v9
	v_bfe_i32 v11, v1, 0, 16
	v_lshlrev_b32_e32 v1, 1, v2
	v_lshrrev_b32_e32 v5, 2, v2
	v_and_b32_e32 v6, 3, v10
	s_mov_b32 s1, 0xfffe0
	v_and_b32_e32 v4, 32, v4
	v_and_b32_e32 v1, 24, v1
	v_and_b32_e32 v5, 4, v5
	v_and_or_b32 v6, v2, s1, v6
	v_or3_b32 v1, v6, v5, v1
	v_add_lshl_u32 v4, v4, v11, 1
	v_add_u32_e32 v0, 0x2000, v0
	v_and_b32_e32 v106, 63, v254
	v_lshrrev_b32_e32 v107, 6, v254
	v_lshrrev_b32_e32 v108, 3, v106
	v_lshl_add_u32 v109, v107, 3, v108
	v_and_b32_e32 v110, 1, v107
	v_bfe_u32 v111, v106, 4, 2
	v_lshl_add_u32 v111, v110, 2, v111
	v_and_b32_e32 v101, 7, v106
	v_xor_b32_e32 v111, v101, v111
	v_lshlrev_b32_e32 v111, 4, v111
	v_lshl_add_u32 v100, v109, 12, v111
	v_add_u32_e32 v101, 0x40000, v100
	v_lshrrev_b32_e32 v109, 5, v106
	v_lshlrev_b32_e32 v109, 3, v109
	v_lshl_add_u32 v109, v110, 4, v109
	v_bfe_u32 v110, v107, 1, 1
	v_lshl_add_u32 v109, v110, 2, v109
	v_and_b32_e32 v110, 3, v108
	v_add_u32_e32 v109, v109, v110
	v_lshrrev_b32_e32 v110, 2, v107
	v_lshl_add_u32 v109, v110, 5, v109
	v_lshl_add_u32 v102, v109, 12, v111
	v_add_u32_e32 v103, 0x40000, v102
	v_and_b32_e32 v106, 15, v254
	v_bfe_u32 v108, v254, 4, 2
	v_bfe_u32 v109, v254, 1, 3
	v_xor_b32_e32 v108, v108, v109
	v_lshlrev_b32_e32 v108, 4, v108
	v_lshl_add_u32 v108, v106, 7, v108
	v_lshrrev_b32_e32 v109, 8, v254
	v_lshl_add_u32 v104, v109, 13, v108
	v_and_b32_e32 v109, 3, v107
	v_lshl_add_u32 v105, v109, 12, v108
	v_mov_b32_e32 v178, v102
	v_ashrrev_i32_e32 v1, 31, v0
	v_lshrrev_b32_e32 v1, 22, v1
	v_add_u32_e32 v1, v0, v1
	v_ashrrev_i32_e32 v12, 10, v1
	v_mul_i32_i24_e32 v1, 0x400, v12
	v_sub_u32_e32 v0, v0, v1
	v_lshrrev_b32_e32 v1, 4, v0
	v_bitop3_b32 v0, v1, v0, 32 bitop3:0x6c
	v_mov_b32_e32 v176, v100
	v_ashrrev_i32_e32 v2, 31, v0
	v_lshrrev_b32_e32 v2, 26, v2
	v_add_u32_e32 v2, v0, v2
	v_lshlrev_b32_e32 v1, 3, v12
	v_ashrrev_i32_e32 v13, 6, v2
	v_and_b32_e32 v2, 0xc0, v2
	v_and_b32_e32 v1, -16, v1
	v_sub_u32_e32 v0, v0, v2
	s_ashr_i32 s0, s8, 6
	v_add_u32_e32 v1, v13, v1
	v_ashrrev_i16_sdwa v0, v3, sext(v0) dst_sel:DWORD dst_unused:UNUSED_PAD src0_sel:DWORD src1_sel:BYTE_0
	v_and_b32_e32 v3, 3, v13
	v_and_or_b32 v3, v1, s1, v3
	s_ashr_i32 s6, s8, 8
	s_lshl_b32 s1, s0, 10
	s_add_u32 s2, s36, 0x2600000
	s_addc_u32 s4, s37, 0
	s_ashr_i32 s61, s60, 31
	s_ashr_i32 s47, s46, 31
	s_lshl_b64 s[14:15], s[60:61], 20
	s_lshl_b64 s[18:19], s[46:47], 20
	s_add_u32 s62, s2, s18
	v_lshlrev_b32_e32 v4, 5, v12
	v_bfe_i32 v14, v0, 0, 16
	v_lshlrev_b32_e32 v0, 1, v1
	v_lshrrev_b32_e32 v2, 2, v1
	s_addc_u32 s63, s4, s19
	s_add_i32 s5, s1, 0
	v_and_b32_e32 v4, 32, v4
	v_and_b32_e32 v0, 24, v0
	v_and_b32_e32 v2, 4, v2
	s_add_i32 m0, s5, 0x10000
	v_or3_b32 v0, v3, v2, v0
	v_add_lshl_u32 v2, v4, v14, 1
	global_load_lds_dwordx4 v178, s[62:63]
	s_add_i32 m0, s5, 0x12000
	v_mov_b32_e32 v182, v103
	s_add_u32 s18, s62, 0x80000
	global_load_lds_dwordx4 v182, s[62:63]
	s_addc_u32 s19, s63, 0
	s_add_i32 m0, s5, 0x14000
	v_mov_b32_e32 v180, v101
	global_load_lds_dwordx4 v178, s[18:19]
	s_add_i32 m0, s5, 0x16000
	s_add_u32 s64, s42, s14
	s_addc_u32 s65, s43, s15
	s_add_i32 s14, s5, 0x2000
	global_load_lds_dwordx4 v182, s[18:19]
	s_mov_b32 m0, s5
	s_add_u32 s18, s64, 0x80000
	global_load_lds_dwordx4 v176, s[64:65]
	s_mov_b32 m0, s14
	s_addc_u32 s19, s65, 0
	s_add_i32 s15, s5, 0x4000
	global_load_lds_dwordx4 v180, s[64:65]
	s_mov_b32 m0, s15
	s_add_i32 s17, s5, 0x6000
	global_load_lds_dwordx4 v176, s[18:19]
	s_mov_b32 m0, s17
	v_mov_b32_e32 v179, 0
	global_load_lds_dwordx4 v180, s[18:19]
	v_mov_b32_e32 v183, v179
	v_mov_b32_e32 v177, v179
	v_mov_b32_e32 v181, v179
	s_cmp_eq_u32 s6, 1
	s_mov_b32 s21, 0
	v_lshl_add_u64 v[6:7], s[62:63], 0, v[178:179]
	v_lshl_add_u64 v[4:5], s[62:63], 0, v[182:183]
	v_lshl_add_u64 v[0:1], s[64:65], 0, v[176:177]
	s_cselect_b64 s[36:37], -1, 0
	s_cmp_lg_u32 s6, 1
	v_lshl_add_u64 v[2:3], s[64:65], 0, v[180:181]
	s_cbranch_scc1 .LBB0_609
	s_barrier
; #define PG8_STAGE(bufoff, gbase, voff) do { _Pragma("unroll") for (int _i = 0; _i < 2; ++_i) \
;         __builtin_amdgcn_global_load_lds((const unsigned*)((const char*)(gbase) + (voff)[_i]), (LAS unsigned*)(lds + (bufoff) + ldsw + _i * 8192), 16, 0, 0); } while (0)
; #define PG8_WAIT_V(n) asm volatile("s_waitcnt vmcnt(" #n ")" ::: "memory")
; #define PG8_BAR __builtin_amdgcn_s_barrier()
; template <class Epi, class Sched>
; __device__ __forceinline__ void gemm_phase(LAS unsigned char* lds, const int K, const int lda, const int ldb, const Sched& S, const Epi& E) {
;     ...
;     const unsigned ldsw = (unsigned)wid * 1024u;
;     const int aoff = lds_byte(wr * 64 + fr, fq * 8), boff = lds_byte(wc * 32 + fr, fq * 8);
;     ...
;     PG8_STAGE(PG8_SB(1, 0), cB + kstep, voffB); PG8_STAGE(PG8_SA(1, 0), cA + kstep, voffA); PG8_STAGE(PG8_SB(1, 1), cB + hB + kstep, voffB);
;     PG8_WAIT_V(6); PG8_BAR;
.LBB0_609:
	s_mov_b64 s[48:49], 0x80
	s_and_b32 s9, s0, 3
	s_add_i32 m0, s5, 0x18000
	v_lshl_add_u64 v[6:7], v[6:7], 0, s[48:49]
	s_lshl_b32 s23, s6, 6
	s_lshl_b32 s18, s6, 13
	s_lshl_b32 s19, s9, 12
	s_waitcnt vmcnt(2)
	s_barrier
	global_load_lds_dwordx4 v[6:7], off
	v_lshl_add_u64 v[4:5], v[4:5], 0, s[48:49]
	s_add_i32 m0, s5, 0x1a000
	s_add_i32 s0, s5, 0x8000
	s_add_i32 s24, s5, 0xa000
	global_load_lds_dwordx4 v[4:5], off
	v_lshl_add_u64 v[0:1], v[0:1], 0, s[48:49]
	s_mov_b32 m0, s0
	s_add_u32 s6, s62, 0x80080
	global_load_lds_dwordx4 v[0:1], off
	v_lshl_add_u64 v[0:1], v[2:3], 0, s[48:49]
	s_mov_b32 m0, s24
	s_addc_u32 s7, s63, 0
	global_load_lds_dwordx4 v[0:1], off
	s_add_i32 m0, s5, 0x1c000
	v_lshl_add_u64 v[0:1], s[6:7], 0, v[178:179]
	global_load_lds_dwordx4 v[0:1], off
	v_lshl_add_u64 v[0:1], s[6:7], 0, v[182:183]
	s_add_i32 m0, s5, 0x1e000
	v_lshrrev_b32_e32 v2, 1, v8
	global_load_lds_dwordx4 v[0:1], off
	v_and_b32_e32 v2, 24, v2
	v_and_b32_e32 v204, 15, v8
	v_and_b32_e32 v3, 48, v8
	v_lshlrev_b32_e32 v4, 2, v8
	v_lshl_or_b32 v206, s9, 5, v2
	v_lshlrev_b32_e32 v2, 15, v12
	v_lshl_or_b32 v3, v204, 6, v3
	v_and_b32_e32 v4, 32, v4
	v_and_b32_e32 v2, 0xffff0000, v2
	v_bitop3_b32 v5, v3, s18, v4 bitop3:0xde
	v_mov_b32_e32 v205, v105
	s_cmpk_lt_u32 s8, 0x100
	v_lshl_add_u32 v2, v13, 12, v2
	v_and_b32_e32 v3, 1, v12
	s_cselect_b64 s[50:51], -1, 0
	s_lshl_b32 s6, s9, 2
	v_lshl_or_b32 v2, v3, 6, v2
	v_and_b32_e32 v0, 63, v8
	v_or_b32_e32 v1, s23, v204
	s_add_i32 s6, s6, 0
	v_mov_b32_e32 v184, v101
	v_lshlrev_b32_e32 v2, 15, v9
	s_add_i32 s19, s6, 0x20000
	v_cmp_gt_u32_e64 s[6:7], 16, v0
	v_lshlrev_b32_e32 v0, 4, v1
	s_movk_i32 s9, 0xffc0
	v_mov_b32_e32 v1, s8
	v_and_b32_e32 v2, 0xffff0000, v2
	v_bfi_b32 v207, s9, v1, v8
	s_ashr_i32 s25, s3, 31
	s_ashr_i32 s26, s33, 31
	v_lshl_add_u32 v2, v10, 12, v2
	v_and_b32_e32 v3, 1, v9
	s_waitcnt vmcnt(6)
	v_lshlrev_b32_e32 v1, 4, v207
	s_waitcnt lgkmcnt(0)
	s_add_u32 s27, s10, 0xf8000000
	v_lshl_or_b32 v2, v3, 6, v2
	s_movk_i32 s18, 0x100
	s_addc_u32 s28, s11, -1
	v_mov_b32_e32 v186, v100
	s_add_i32 s29, 0, 0x10000
	s_add_i32 s34, 0, 0x14000
	v_mbcnt_lo_u32_b32 v2, -1, 0
	v_add_u32_e32 v1, 0, v1
	v_cmp_gt_i32_e64 s[8:9], s18, v207
	v_mov_b32_e32 v185, v179
	v_mov_b32_e32 v187, v179
	v_mov_b64_e32 v[188:189], 0x400
	v_mov_b64_e32 v[190:191], 0x3ff
	v_add_u32_e32 v208, s29, v205
	v_add_u32_e32 v209, s34, v205
	v_mov_b32_e32 v210, v104
	v_xor_b32_e32 v234, 64, v210
	v_xor_b32_e32 v235, 64, v208
	v_xor_b32_e32 v236, 64, v209
	v_xor_b32_e32 v237, 64, v205
	v_mbcnt_hi_u32_b32 v211, -1, v2
	v_add_u32_e32 v212, 0x20000, v1
	v_add_u32_e32 v213, s19, v0
	s_barrier
	s_branch .LBB0_612

; #define PG8_STAGE(bufoff, gbase, voff) do { _Pragma("unroll") for (int _i = 0; _i < 2; ++_i) \
;         __builtin_amdgcn_global_load_lds((const unsigned*)((const char*)(gbase) + (voff)[_i]), (LAS unsigned*)(lds + (bufoff) + ldsw + _i * 8192), 16, 0, 0); } while (0)
; #define PG8_LDA(dst, b, h) do { _Pragma("unroll") for (int m = 0; m < 4; ++m) _Pragma("unroll") for (int k = 0; k < 2; ++k) dst[m][k] = *(const LAS bf16x8*)(lds + PG8_SA(b, h) + aoff + m * 2048 + k * 1024); } while (0)
; #define PG8_LDB(dst, b, h) do { _Pragma("unroll") for (int n = 0; n < 2; ++n) _Pragma("unroll") for (int k = 0; k < 2; ++k) dst[n][k] = *(const LAS bf16x8*)(lds + PG8_SB(b, h) + boff + n * 2048 + k * 1024); } while (0)
; #define PG8_MMA(ai, bj, At, Bt) do { __builtin_amdgcn_s_setprio(1); _Pragma("unroll") for (int m = 0; m < 4; ++m) _Pragma("unroll") for (int n = 0; n < 2; ++n) _Pragma("unroll") for (int k = 0; k < 2; ++k) \
;         acc[ai][bj][m][n] = __builtin_amdgcn_mfma_f32_16x16x32_bf16(Bt[n][k], At[m][k], acc[ai][bj][m][n], 0, 0, 0); __builtin_amdgcn_s_setprio(0); } while (0)
; #define PG8_WAIT_V(n) asm volatile("s_waitcnt vmcnt(" #n ")" ::: "memory")
; #define PG8_WAIT_L(n) asm volatile("s_waitcnt lgkmcnt(" #n ")" ::: "memory")
; #define PG8_BAR __builtin_amdgcn_s_barrier()
; #define PG8_SCHED __builtin_amdgcn_sched_barrier(0)
; template <class Epi, class Sched>
; __device__ __forceinline__ void gemm_phase(LAS unsigned char* lds, const int K, const int lda, const int ldb, const Sched& S, const Epi& E) {
;     ...
;             PG8_LDB(B0, 0, 0); PG8_LDB(B1, 0, 1); PG8_SCHED; PG8_LDA(At, 0, 0); PG8_STAGE(PG8_SA(1, 1), a1 + hA, voffA);
;             PG8_WAIT_V(8); PG8_WAIT_L(0); PG8_BAR; PG8_MMA(0, 0, At, B0); PG8_MMA(0, 1, At, B1); PG8_BAR; PG8_SCHED;
;             PG8_LDA(At, 0, 1); PG8_STAGE(PG8_SB(0, 0), b2, voffB); PG8_STAGE(PG8_SB(0, 1), b2 + hB, voffB); PG8_STAGE(PG8_SA(0, 0), a2, voffA);
.LBB0_619:
	ds_read_b128 v[128:131], v208
	ds_read_b128 v[132:135], v235
	ds_read_b128 v[136:139], v208 offset:2048
	ds_read_b128 v[140:143], v235 offset:2048
	ds_read_b128 v[144:147], v209
	ds_read_b128 v[148:151], v236
	ds_read_b128 v[152:155], v209 offset:2048
	ds_read_b128 v[156:159], v236 offset:2048
	s_add_u32 s53, s62, 0xfff80080
	s_addc_u32 s55, s63, -1
	s_cmp_eq_u32 s47, 28
	s_cselect_b32 s67, s18, s55
	s_cselect_b32 s66, s19, s53
	s_cselect_b32 s65, s35, s41
	s_cselect_b32 s64, s38, s39
	v_lshl_add_u64 v[218:219], s[62:63], 0, v[186:187]
	s_add_i32 m0, s5, 0xc000
	ds_read_b128 v[160:163], v210
	ds_read_b128 v[164:167], v234
	ds_read_b128 v[168:171], v210 offset:2048
	ds_read_b128 v[172:175], v234 offset:2048
	ds_read_b128 v[192:195], v210 offset:4096
	ds_read_b128 v[196:199], v234 offset:4096
	ds_read_b128 v[200:203], v210 offset:6144
	ds_read_b128 v[214:217], v234 offset:6144
	global_load_lds_dwordx4 v[218:219], off
	v_lshl_add_u64 v[218:219], s[62:63], 0, v[184:185]
	s_add_i32 m0, s5, 0xe000
	s_nop 0
	global_load_lds_dwordx4 v[218:219], off
	s_waitcnt vmcnt(8)
	s_waitcnt lgkmcnt(0)
	s_barrier
	s_setprio 1
	s_waitcnt lgkmcnt(0)
	v_mfma_f32_16x16x32_bf16 v[124:127], v[128:131], v[160:163], v[124:127]
	v_mfma_f32_16x16x32_bf16 v[120:123], v[136:139], v[160:163], v[120:123]
	v_mfma_f32_16x16x32_bf16 v[108:111], v[128:131], v[168:171], v[108:111]
	v_mfma_f32_16x16x32_bf16 v[104:107], v[136:139], v[168:171], v[104:107]
	v_mfma_f32_16x16x32_bf16 v[92:95], v[128:131], v[192:195], v[92:95]
	v_mfma_f32_16x16x32_bf16 v[88:91], v[136:139], v[192:195], v[88:91]
	v_mfma_f32_16x16x32_bf16 v[76:79], v[128:131], v[200:203], v[76:79]
	v_mfma_f32_16x16x32_bf16 v[72:75], v[136:139], v[200:203], v[72:75]
	v_mfma_f32_16x16x32_bf16 v[124:127], v[132:135], v[164:167], v[124:127]
	v_mfma_f32_16x16x32_bf16 v[120:123], v[140:143], v[164:167], v[120:123]
	v_mfma_f32_16x16x32_bf16 v[108:111], v[132:135], v[172:175], v[108:111]
	v_mfma_f32_16x16x32_bf16 v[104:107], v[140:143], v[172:175], v[104:107]
	v_mfma_f32_16x16x32_bf16 v[92:95], v[132:135], v[196:199], v[92:95]
	v_mfma_f32_16x16x32_bf16 v[88:91], v[140:143], v[196:199], v[88:91]
	v_mfma_f32_16x16x32_bf16 v[76:79], v[132:135], v[214:217], v[76:79]
	v_mfma_f32_16x16x32_bf16 v[72:75], v[140:143], v[214:217], v[72:75]
	s_setprio 0
	s_setprio 1
	v_mfma_f32_16x16x32_bf16 v[116:119], v[144:147], v[160:163], v[116:119]
	v_mfma_f32_16x16x32_bf16 v[112:115], v[152:155], v[160:163], v[112:115]
	v_mfma_f32_16x16x32_bf16 v[100:103], v[144:147], v[168:171], v[100:103]
	v_mfma_f32_16x16x32_bf16 v[96:99], v[152:155], v[168:171], v[96:99]
	v_mfma_f32_16x16x32_bf16 v[84:87], v[144:147], v[192:195], v[84:87]
	v_mfma_f32_16x16x32_bf16 v[80:83], v[152:155], v[192:195], v[80:83]
	v_mfma_f32_16x16x32_bf16 v[68:71], v[144:147], v[200:203], v[68:71]
	v_mfma_f32_16x16x32_bf16 v[64:67], v[152:155], v[200:203], v[64:67]
	v_mfma_f32_16x16x32_bf16 v[116:119], v[148:151], v[164:167], v[116:119]
	v_mfma_f32_16x16x32_bf16 v[112:115], v[156:159], v[164:167], v[112:115]
	v_mfma_f32_16x16x32_bf16 v[100:103], v[148:151], v[172:175], v[100:103]
	v_mfma_f32_16x16x32_bf16 v[96:99], v[156:159], v[172:175], v[96:99]
	v_mfma_f32_16x16x32_bf16 v[84:87], v[148:151], v[196:199], v[84:87]
	v_mfma_f32_16x16x32_bf16 v[80:83], v[156:159], v[196:199], v[80:83]
	v_mfma_f32_16x16x32_bf16 v[68:71], v[148:151], v[214:217], v[68:71]
	v_mfma_f32_16x16x32_bf16 v[64:67], v[156:159], v[214:217], v[64:67]
	s_setprio 0
	s_barrier
	s_add_i32 s53, s29, s1
	v_lshl_add_u64 v[218:219], s[64:65], 0, v[178:179]
	s_mov_b32 m0, s53
	ds_read_b128 v[160:163], v210 offset:16384
	ds_read_b128 v[164:167], v234 offset:16384
	ds_read_b128 v[168:171], v210 offset:18432
	ds_read_b128 v[172:175], v234 offset:18432
	ds_read_b128 v[192:195], v210 offset:20480
	ds_read_b128 v[196:199], v234 offset:20480
	ds_read_b128 v[200:203], v210 offset:22528
	ds_read_b128 v[214:217], v234 offset:22528
	global_load_lds_dwordx4 v[218:219], off
	s_add_i32 m0, s53, 0x2000
	s_add_u32 s68, s64, 0x80000
	v_lshl_add_u64 v[220:221], s[64:65], 0, v[182:183]
	s_addc_u32 s69, s65, 0
	s_add_i32 s53, s34, s1
	global_load_lds_dwordx4 v[220:221], off
	v_lshl_add_u64 v[222:223], s[68:69], 0, v[178:179]
	s_mov_b32 m0, s53
	v_lshl_add_u64 v[224:225], s[66:67], 0, v[180:181]
	global_load_lds_dwordx4 v[222:223], off
	v_lshl_add_u64 v[222:223], s[68:69], 0, v[182:183]
	s_add_i32 m0, s53, 0x2000
	s_nop 0
	global_load_lds_dwordx4 v[222:223], off
	v_lshl_add_u64 v[222:223], s[66:67], 0, v[176:177]
	s_mov_b32 m0, s5
	s_nop 0
	global_load_lds_dwordx4 v[222:223], off
	s_mov_b32 m0, s14
	s_nop 0
	global_load_lds_dwordx4 v[224:225], off
	s_waitcnt vmcnt(8)
	s_waitcnt lgkmcnt(0)
	s_barrier
; #define PG8_STAGE(bufoff, gbase, voff) do { _Pragma("unroll") for (int _i = 0; _i < 2; ++_i) \
;         __builtin_amdgcn_global_load_lds((const unsigned*)((const char*)(gbase) + (voff)[_i]), (LAS unsigned*)(lds + (bufoff) + ldsw + _i * 8192), 16, 0, 0); } while (0)
; #define PG8_LDA(dst, b, h) do { _Pragma("unroll") for (int m = 0; m < 4; ++m) _Pragma("unroll") for (int k = 0; k < 2; ++k) dst[m][k] = *(const LAS bf16x8*)(lds + PG8_SA(b, h) + aoff + m * 2048 + k * 1024); } while (0)
; #define PG8_LDB(dst, b, h) do { _Pragma("unroll") for (int n = 0; n < 2; ++n) _Pragma("unroll") for (int k = 0; k < 2; ++k) dst[n][k] = *(const LAS bf16x8*)(lds + PG8_SB(b, h) + boff + n * 2048 + k * 1024); } while (0)
; #define PG8_MMA(ai, bj, At, Bt) do { __builtin_amdgcn_s_setprio(1); _Pragma("unroll") for (int m = 0; m < 4; ++m) _Pragma("unroll") for (int n = 0; n < 2; ++n) _Pragma("unroll") for (int k = 0; k < 2; ++k) \
;         acc[ai][bj][m][n] = __builtin_amdgcn_mfma_f32_16x16x32_bf16(Bt[n][k], At[m][k], acc[ai][bj][m][n], 0, 0, 0); __builtin_amdgcn_s_setprio(0); } while (0)
; #define PG8_WAIT_V(n) asm volatile("s_waitcnt vmcnt(" #n ")" ::: "memory")
; #define PG8_WAIT_L(n) asm volatile("s_waitcnt lgkmcnt(" #n ")" ::: "memory")
; #define PG8_BAR __builtin_amdgcn_s_barrier()
; #define PG8_SCHED __builtin_amdgcn_sched_barrier(0)
; template <class Epi, class Sched>
; __device__ __forceinline__ void gemm_phase(LAS unsigned char* lds, const int K, const int lda, const int ldb, const Sched& S, const Epi& E) {
;     ...
;             PG8_WAIT_V(8); PG8_WAIT_L(0); PG8_BAR; PG8_MMA(1, 0, At, B0); PG8_MMA(1, 1, At, B1); PG8_BAR; PG8_SCHED;
;             PG8_LDB(B0, 1, 0); PG8_LDB(B1, 1, 1); PG8_SCHED; PG8_LDA(At, 1, 0); PG8_STAGE(PG8_SA(0, 1), a2 + hA, voffA);
;             PG8_WAIT_V(8); PG8_WAIT_L(0); PG8_BAR; PG8_MMA(0, 0, At, B0); PG8_MMA(0, 1, At, B1); PG8_BAR; PG8_SCHED;
	s_setprio 1
	s_waitcnt lgkmcnt(0)
	v_mfma_f32_16x16x32_bf16 v[60:63], v[128:131], v[160:163], v[60:63]
	v_mfma_f32_16x16x32_bf16 v[56:59], v[136:139], v[160:163], v[56:59]
	v_mfma_f32_16x16x32_bf16 v[44:47], v[128:131], v[168:171], v[44:47]
	v_mfma_f32_16x16x32_bf16 v[40:43], v[136:139], v[168:171], v[40:43]
	v_mfma_f32_16x16x32_bf16 v[28:31], v[128:131], v[192:195], v[28:31]
	v_mfma_f32_16x16x32_bf16 v[24:27], v[136:139], v[192:195], v[24:27]
	v_mfma_f32_16x16x32_bf16 v[12:15], v[128:131], v[200:203], v[12:15]
	v_mfma_f32_16x16x32_bf16 v[8:11], v[136:139], v[200:203], v[8:11]
	v_mfma_f32_16x16x32_bf16 v[60:63], v[132:135], v[164:167], v[60:63]
	v_mfma_f32_16x16x32_bf16 v[56:59], v[140:143], v[164:167], v[56:59]
	v_mfma_f32_16x16x32_bf16 v[44:47], v[132:135], v[172:175], v[44:47]
	v_mfma_f32_16x16x32_bf16 v[40:43], v[140:143], v[172:175], v[40:43]
	v_mfma_f32_16x16x32_bf16 v[28:31], v[132:135], v[196:199], v[28:31]
	v_mfma_f32_16x16x32_bf16 v[24:27], v[140:143], v[196:199], v[24:27]
	v_mfma_f32_16x16x32_bf16 v[12:15], v[132:135], v[214:217], v[12:15]
	v_mfma_f32_16x16x32_bf16 v[8:11], v[140:143], v[214:217], v[8:11]
	s_setprio 0
	s_setprio 1
	v_mfma_f32_16x16x32_bf16 v[52:55], v[144:147], v[160:163], v[52:55]
	v_mfma_f32_16x16x32_bf16 v[48:51], v[152:155], v[160:163], v[48:51]
	v_mfma_f32_16x16x32_bf16 v[36:39], v[144:147], v[168:171], v[36:39]
	v_mfma_f32_16x16x32_bf16 v[32:35], v[152:155], v[168:171], v[32:35]
	v_mfma_f32_16x16x32_bf16 v[20:23], v[144:147], v[192:195], v[20:23]
	v_mfma_f32_16x16x32_bf16 v[16:19], v[152:155], v[192:195], v[16:19]
	v_mfma_f32_16x16x32_bf16 v[4:7], v[144:147], v[200:203], v[4:7]
	v_mfma_f32_16x16x32_bf16 v[0:3], v[152:155], v[200:203], v[0:3]
	v_mfma_f32_16x16x32_bf16 v[52:55], v[148:151], v[164:167], v[52:55]
	v_mfma_f32_16x16x32_bf16 v[48:51], v[156:159], v[164:167], v[48:51]
	v_mfma_f32_16x16x32_bf16 v[36:39], v[148:151], v[172:175], v[36:39]
	v_mfma_f32_16x16x32_bf16 v[32:35], v[156:159], v[172:175], v[32:35]
	v_mfma_f32_16x16x32_bf16 v[20:23], v[148:151], v[196:199], v[20:23]
	v_mfma_f32_16x16x32_bf16 v[16:19], v[156:159], v[196:199], v[16:19]
	v_mfma_f32_16x16x32_bf16 v[4:7], v[148:151], v[214:217], v[4:7]
	v_mfma_f32_16x16x32_bf16 v[0:3], v[156:159], v[214:217], v[0:3]
	s_setprio 0
	s_barrier
	s_add_i32 s53, 0, 0x18000
	s_add_i32 s55, 0, 0x1c000
	v_add_u32_e32 v140, s53, v205
	v_add_u32_e32 v238, s53, v237
	v_add_u32_e32 v156, s55, v205
	v_add_u32_e32 v239, s55, v237
	ds_read_b128 v[128:131], v140
	ds_read_b128 v[132:135], v238
	ds_read_b128 v[136:139], v140 offset:2048
	ds_read_b128 v[140:143], v238 offset:2048
	ds_read_b128 v[144:147], v156
	ds_read_b128 v[148:151], v239
	ds_read_b128 v[152:155], v156 offset:2048
	ds_read_b128 v[156:159], v239 offset:2048
	s_add_u32 s66, s66, 0x80000
	s_addc_u32 s67, s67, 0
	s_mov_b32 m0, s15
	v_lshl_add_u64 v[226:227], s[66:67], 0, v[176:177]
	ds_read_b128 v[160:163], v210 offset:32768
	ds_read_b128 v[164:167], v234 offset:32768
	ds_read_b128 v[168:171], v210 offset:34816
	ds_read_b128 v[172:175], v234 offset:34816
	ds_read_b128 v[192:195], v210 offset:36864
	ds_read_b128 v[196:199], v234 offset:36864
	ds_read_b128 v[200:203], v210 offset:38912
	ds_read_b128 v[214:217], v234 offset:38912
	global_load_lds_dwordx4 v[226:227], off
	v_lshl_add_u64 v[226:227], s[66:67], 0, v[180:181]
	s_mov_b32 m0, s17
	s_nop 0
	global_load_lds_dwordx4 v[226:227], off
	s_waitcnt vmcnt(8)
	s_waitcnt lgkmcnt(0)
	s_barrier
	s_setprio 1
	s_waitcnt lgkmcnt(0)
	v_mfma_f32_16x16x32_bf16 v[124:127], v[128:131], v[160:163], v[124:127]
	v_mfma_f32_16x16x32_bf16 v[120:123], v[136:139], v[160:163], v[120:123]
	v_mfma_f32_16x16x32_bf16 v[108:111], v[128:131], v[168:171], v[108:111]
	v_mfma_f32_16x16x32_bf16 v[104:107], v[136:139], v[168:171], v[104:107]
	v_mfma_f32_16x16x32_bf16 v[92:95], v[128:131], v[192:195], v[92:95]
	v_mfma_f32_16x16x32_bf16 v[88:91], v[136:139], v[192:195], v[88:91]
	v_mfma_f32_16x16x32_bf16 v[76:79], v[128:131], v[200:203], v[76:79]
	v_mfma_f32_16x16x32_bf16 v[72:75], v[136:139], v[200:203], v[72:75]
	v_mfma_f32_16x16x32_bf16 v[124:127], v[132:135], v[164:167], v[124:127]
	v_mfma_f32_16x16x32_bf16 v[120:123], v[140:143], v[164:167], v[120:123]
	v_mfma_f32_16x16x32_bf16 v[108:111], v[132:135], v[172:175], v[108:111]
	v_mfma_f32_16x16x32_bf16 v[104:107], v[140:143], v[172:175], v[104:107]
	v_mfma_f32_16x16x32_bf16 v[92:95], v[132:135], v[196:199], v[92:95]
	v_mfma_f32_16x16x32_bf16 v[88:91], v[140:143], v[196:199], v[88:91]
	v_mfma_f32_16x16x32_bf16 v[76:79], v[132:135], v[214:217], v[76:79]
	v_mfma_f32_16x16x32_bf16 v[72:75], v[140:143], v[214:217], v[72:75]
	s_setprio 0
	s_setprio 1
	v_mfma_f32_16x16x32_bf16 v[116:119], v[144:147], v[160:163], v[116:119]
	v_mfma_f32_16x16x32_bf16 v[112:115], v[152:155], v[160:163], v[112:115]
	v_mfma_f32_16x16x32_bf16 v[100:103], v[144:147], v[168:171], v[100:103]
	v_mfma_f32_16x16x32_bf16 v[96:99], v[152:155], v[168:171], v[96:99]
	v_mfma_f32_16x16x32_bf16 v[84:87], v[144:147], v[192:195], v[84:87]
	v_mfma_f32_16x16x32_bf16 v[80:83], v[152:155], v[192:195], v[80:83]
	v_mfma_f32_16x16x32_bf16 v[68:71], v[144:147], v[200:203], v[68:71]
	v_mfma_f32_16x16x32_bf16 v[64:67], v[152:155], v[200:203], v[64:67]
	v_mfma_f32_16x16x32_bf16 v[116:119], v[148:151], v[164:167], v[116:119]
	v_mfma_f32_16x16x32_bf16 v[112:115], v[156:159], v[164:167], v[112:115]
	v_mfma_f32_16x16x32_bf16 v[100:103], v[148:151], v[172:175], v[100:103]
	v_mfma_f32_16x16x32_bf16 v[96:99], v[156:159], v[172:175], v[96:99]
	v_mfma_f32_16x16x32_bf16 v[84:87], v[148:151], v[196:199], v[84:87]
	v_mfma_f32_16x16x32_bf16 v[80:83], v[156:159], v[196:199], v[80:83]
	v_mfma_f32_16x16x32_bf16 v[68:71], v[148:151], v[214:217], v[68:71]
	v_mfma_f32_16x16x32_bf16 v[64:67], v[156:159], v[214:217], v[64:67]
	s_setprio 0
	s_barrier
; #define PG8_STAGE(bufoff, gbase, voff) do { _Pragma("unroll") for (int _i = 0; _i < 2; ++_i) \
;         __builtin_amdgcn_global_load_lds((const unsigned*)((const char*)(gbase) + (voff)[_i]), (LAS unsigned*)(lds + (bufoff) + ldsw + _i * 8192), 16, 0, 0); } while (0)
; #define PG8_LDA(dst, b, h) do { _Pragma("unroll") for (int m = 0; m < 4; ++m) _Pragma("unroll") for (int k = 0; k < 2; ++k) dst[m][k] = *(const LAS bf16x8*)(lds + PG8_SA(b, h) + aoff + m * 2048 + k * 1024); } while (0)
; #define PG8_MMA(ai, bj, At, Bt) do { __builtin_amdgcn_s_setprio(1); _Pragma("unroll") for (int m = 0; m < 4; ++m) _Pragma("unroll") for (int n = 0; n < 2; ++n) _Pragma("unroll") for (int k = 0; k < 2; ++k) \
;         acc[ai][bj][m][n] = __builtin_amdgcn_mfma_f32_16x16x32_bf16(Bt[n][k], At[m][k], acc[ai][bj][m][n], 0, 0, 0); __builtin_amdgcn_s_setprio(0); } while (0)
; #define PG8_WAIT_V(n) asm volatile("s_waitcnt vmcnt(" #n ")" ::: "memory")
; #define PG8_WAIT_L(n) asm volatile("s_waitcnt lgkmcnt(" #n ")" ::: "memory")
; #define PG8_BAR __builtin_amdgcn_s_barrier()
; #define PG8_SCHED __builtin_amdgcn_sched_barrier(0)
; template <class Epi, class Sched>
; __device__ __forceinline__ void gemm_phase(LAS unsigned char* lds, const int K, const int lda, const int ldb, const Sched& S, const Epi& E) {
;     ...
;             PG8_LDA(At, 1, 1); PG8_STAGE(PG8_SB(1, 0), b3, voffB); PG8_STAGE(PG8_SB(1, 1), b3 + hB, voffB); PG8_STAGE(PG8_SA(1, 0), a3, voffA);
;             PG8_WAIT_V(8); PG8_WAIT_L(0); PG8_BAR; PG8_MMA(1, 0, At, B0); PG8_MMA(1, 1, At, B1); PG8_BAR; PG8_SCHED;
;         }
	s_add_i32 s53, s53, s1
	v_lshl_add_u64 v[218:219], v[218:219], 0, s[48:49]
	s_mov_b32 m0, s53
	ds_read_b128 v[160:163], v210 offset:49152
	ds_read_b128 v[164:167], v234 offset:49152
	ds_read_b128 v[168:171], v210 offset:51200
	ds_read_b128 v[172:175], v234 offset:51200
	ds_read_b128 v[192:195], v210 offset:53248
	ds_read_b128 v[196:199], v234 offset:53248
	ds_read_b128 v[200:203], v210 offset:55296
	ds_read_b128 v[214:217], v234 offset:55296
	global_load_lds_dwordx4 v[218:219], off
	s_add_i32 m0, s53, 0x2000
	s_add_u32 s64, s64, 0x80080
	v_lshl_add_u64 v[218:219], v[220:221], 0, s[48:49]
	s_addc_u32 s65, s65, 0
	s_add_i32 s53, s55, s1
	global_load_lds_dwordx4 v[218:219], off
	v_lshl_add_u64 v[218:219], s[64:65], 0, v[178:179]
	s_mov_b32 m0, s53
	s_nop 0
	global_load_lds_dwordx4 v[218:219], off
	v_lshl_add_u64 v[218:219], s[64:65], 0, v[182:183]
	s_add_i32 m0, s53, 0x2000
	s_nop 0
	global_load_lds_dwordx4 v[218:219], off
	v_lshl_add_u64 v[218:219], v[222:223], 0, s[48:49]
	s_mov_b32 m0, s0
	s_nop 0
	global_load_lds_dwordx4 v[218:219], off
	v_lshl_add_u64 v[218:219], v[224:225], 0, s[48:49]
	s_mov_b32 m0, s24
	s_nop 0
	global_load_lds_dwordx4 v[218:219], off
	s_waitcnt vmcnt(8)
	s_waitcnt lgkmcnt(0)
	s_barrier
	s_setprio 1
	s_waitcnt lgkmcnt(0)
	v_mfma_f32_16x16x32_bf16 v[60:63], v[128:131], v[160:163], v[60:63]
	v_mfma_f32_16x16x32_bf16 v[56:59], v[136:139], v[160:163], v[56:59]
	v_mfma_f32_16x16x32_bf16 v[44:47], v[128:131], v[168:171], v[44:47]
	v_mfma_f32_16x16x32_bf16 v[40:43], v[136:139], v[168:171], v[40:43]
	v_mfma_f32_16x16x32_bf16 v[28:31], v[128:131], v[192:195], v[28:31]
	v_mfma_f32_16x16x32_bf16 v[24:27], v[136:139], v[192:195], v[24:27]
	v_mfma_f32_16x16x32_bf16 v[12:15], v[128:131], v[200:203], v[12:15]
	v_mfma_f32_16x16x32_bf16 v[8:11], v[136:139], v[200:203], v[8:11]
	v_mfma_f32_16x16x32_bf16 v[60:63], v[132:135], v[164:167], v[60:63]
	v_mfma_f32_16x16x32_bf16 v[56:59], v[140:143], v[164:167], v[56:59]
	v_mfma_f32_16x16x32_bf16 v[44:47], v[132:135], v[172:175], v[44:47]
	v_mfma_f32_16x16x32_bf16 v[40:43], v[140:143], v[172:175], v[40:43]
	v_mfma_f32_16x16x32_bf16 v[28:31], v[132:135], v[196:199], v[28:31]
	v_mfma_f32_16x16x32_bf16 v[24:27], v[140:143], v[196:199], v[24:27]
	v_mfma_f32_16x16x32_bf16 v[12:15], v[132:135], v[214:217], v[12:15]
	v_mfma_f32_16x16x32_bf16 v[8:11], v[140:143], v[214:217], v[8:11]
	s_setprio 0
	s_setprio 1
	v_mfma_f32_16x16x32_bf16 v[52:55], v[144:147], v[160:163], v[52:55]
	v_mfma_f32_16x16x32_bf16 v[48:51], v[152:155], v[160:163], v[48:51]
	v_mfma_f32_16x16x32_bf16 v[36:39], v[144:147], v[168:171], v[36:39]
	v_mfma_f32_16x16x32_bf16 v[32:35], v[152:155], v[168:171], v[32:35]
	v_mfma_f32_16x16x32_bf16 v[20:23], v[144:147], v[192:195], v[20:23]
	v_mfma_f32_16x16x32_bf16 v[16:19], v[152:155], v[192:195], v[16:19]
	v_mfma_f32_16x16x32_bf16 v[4:7], v[144:147], v[200:203], v[4:7]
	v_mfma_f32_16x16x32_bf16 v[0:3], v[152:155], v[200:203], v[0:3]
	v_mfma_f32_16x16x32_bf16 v[52:55], v[148:151], v[164:167], v[52:55]
	v_mfma_f32_16x16x32_bf16 v[48:51], v[156:159], v[164:167], v[48:51]
	v_mfma_f32_16x16x32_bf16 v[36:39], v[148:151], v[172:175], v[36:39]
	v_mfma_f32_16x16x32_bf16 v[32:35], v[156:159], v[172:175], v[32:35]
	v_mfma_f32_16x16x32_bf16 v[20:23], v[148:151], v[196:199], v[20:23]
	v_mfma_f32_16x16x32_bf16 v[16:19], v[156:159], v[196:199], v[16:19]
	v_mfma_f32_16x16x32_bf16 v[4:7], v[148:151], v[214:217], v[4:7]
	v_mfma_f32_16x16x32_bf16 v[0:3], v[156:159], v[214:217], v[0:3]
	s_setprio 0
	s_barrier
	s_add_i32 s47, s47, 2
	s_add_u32 s39, s39, 0x100
	s_addc_u32 s41, s41, 0
	s_add_u32 s62, s62, 0x100
	s_addc_u32 s63, s63, 0
	s_cmp_gt_u32 s47, 29
	s_cbranch_scc0 .LBB0_619
	s_and_b64 vcc, exec, s[50:51]
	s_cbranch_vccz .LBB0_622
	s_barrier

; #define PG8_STAGE(bufoff, gbase, voff) do { _Pragma("unroll") for (int _i = 0; _i < 2; ++_i) \
;         __builtin_amdgcn_global_load_lds((const unsigned*)((const char*)(gbase) + (voff)[_i]), (LAS unsigned*)(lds + (bufoff) + ldsw + _i * 8192), 16, 0, 0); } while (0)
; #define PG8_WAIT_V(n) asm volatile("s_waitcnt vmcnt(" #n ")" ::: "memory")
; #define PG8_BAR __builtin_amdgcn_s_barrier()
; template <class Epi, class Sched>
; __device__ __forceinline__ void gemm_phase(LAS unsigned char* lds, const int K, const int lda, const int ldb, const Sched& S, const Epi& E) {
;     ...
;     for (int i = 0; i < 2; ++i) { int R, C; stage_rc(tid * 16 + i * 8192, R, C); const int Rb = (R & ~31) + perm32(R & 31);
;         voffA[i] = (unsigned)(R * lda + C) * 2u; voffB[i] = (unsigned)(Rb * ldb + C) * 2u; }
;     const size_t kstep = (size_t)(BK * 2);
;     const size_t hA = (size_t)HALF * lda * 2, hB = (size_t)HALF * ldb * 2;
;     const unsigned ldsw = (unsigned)wid * 1024u;
;     const int aoff = lds_byte(wr * 64 + fr, fq * 8), boff = lds_byte(wc * 32 + fr, fq * 8);
;     ...
;     const char* cA = S.aptr(cur); const char* cB = S.bptr(cur);
;     PG8_STAGE(PG8_SB(0, 0), cB, voffB); PG8_STAGE(PG8_SB(0, 1), cB + hB, voffB); PG8_STAGE(PG8_SA(0, 0), cA, voffA); PG8_STAGE(PG8_SA(0, 1), cA + hA, voffA);
;     if (wr == 1) PG8_BAR;
;     PG8_WAIT_V(2); PG8_BAR;
.LBB0_876:
	v_readlane_b32 s4, v255, 24
	v_readlane_b32 s5, v255, 25
	s_and_b64 vcc, exec, s[4:5]
	s_cbranch_vccnz .LBB0_914
	v_ashrrev_i32_e32 v1, 31, v8
	v_lshrrev_b32_e32 v1, 26, v1
	v_add_u32_e32 v1, v8, v1
	v_ashrrev_i32_e32 v9, 6, v1
	v_bfe_i32 v1, v8, 27, 1
	v_lshlrev_b32_e32 v0, 4, v8
	v_lshrrev_b32_e32 v1, 22, v1
	v_add_u32_e32 v1, v0, v1
	v_and_b32_e32 v1, 0xfffffc00, v1
	v_sub_u32_e32 v1, v0, v1
	v_lshrrev_b32_e32 v2, 4, v1
	v_bitop3_b32 v1, v2, v1, 32 bitop3:0x6c
	v_ashrrev_i32_e32 v3, 31, v1
	v_lshrrev_b32_e32 v3, 26, v3
	v_add_u32_e32 v3, v1, v3
	v_lshlrev_b32_e32 v2, 3, v9
	v_ashrrev_i32_e32 v10, 6, v3
	v_and_b32_e32 v3, 0xc0, v3
	v_and_b32_e32 v2, -16, v2
	v_sub_u32_e32 v1, v1, v3
	v_mov_b32_e32 v3, 1
	v_add_u32_e32 v2, v10, v2
	v_ashrrev_i16_sdwa v1, v3, sext(v1) dst_sel:DWORD dst_unused:UNUSED_PAD src0_sel:DWORD src1_sel:BYTE_0
	v_lshlrev_b32_e32 v4, 5, v9
	v_bfe_i32 v11, v1, 0, 16
	v_lshlrev_b32_e32 v1, 1, v2
	v_lshrrev_b32_e32 v5, 2, v2
	v_and_b32_e32 v6, 3, v10
	s_mov_b32 s1, 0xfffe0
	v_and_b32_e32 v4, 32, v4
	v_and_b32_e32 v1, 24, v1
	v_and_b32_e32 v5, 4, v5
	v_and_or_b32 v6, v2, s1, v6
	v_or3_b32 v1, v6, v5, v1
	v_add_lshl_u32 v4, v4, v11, 1
	v_add_u32_e32 v0, 0x2000, v0
	v_and_b32_e32 v106, 63, v254
	v_lshrrev_b32_e32 v107, 6, v254
	v_lshrrev_b32_e32 v108, 3, v106
	v_lshl_add_u32 v109, v107, 3, v108
	v_and_b32_e32 v110, 1, v107
	v_bfe_u32 v111, v106, 4, 2
	v_lshl_add_u32 v111, v110, 2, v111
	v_and_b32_e32 v101, 7, v106
	v_xor_b32_e32 v111, v101, v111
	v_lshlrev_b32_e32 v111, 4, v111
	v_lshl_add_u32 v100, v109, 12, v111
	v_add_u32_e32 v101, 0x40000, v100
	v_lshrrev_b32_e32 v109, 5, v106
	v_lshlrev_b32_e32 v109, 3, v109
	v_lshl_add_u32 v109, v110, 4, v109
	v_bfe_u32 v110, v107, 1, 1
	v_lshl_add_u32 v109, v110, 2, v109
	v_and_b32_e32 v110, 3, v108
	v_add_u32_e32 v109, v109, v110
	v_lshrrev_b32_e32 v110, 2, v107
	v_lshl_add_u32 v109, v110, 5, v109
	v_lshl_add_u32 v102, v109, 12, v111
	v_add_u32_e32 v103, 0x40000, v102
	v_and_b32_e32 v106, 15, v254
	v_bfe_u32 v108, v254, 4, 2
	v_bfe_u32 v109, v254, 1, 3
	v_xor_b32_e32 v108, v108, v109
	v_lshlrev_b32_e32 v108, 4, v108
	v_lshl_add_u32 v108, v106, 7, v108
	v_lshrrev_b32_e32 v109, 8, v254
	v_lshl_add_u32 v104, v109, 13, v108
	v_and_b32_e32 v109, 3, v107
	v_lshl_add_u32 v105, v109, 12, v108
	v_mov_b32_e32 v186, v102
	v_ashrrev_i32_e32 v1, 31, v0
	v_lshrrev_b32_e32 v1, 22, v1
	v_add_u32_e32 v1, v0, v1
	v_ashrrev_i32_e32 v12, 10, v1
	v_mul_i32_i24_e32 v1, 0x400, v12
	v_sub_u32_e32 v0, v0, v1
	v_lshrrev_b32_e32 v1, 4, v0
	v_bitop3_b32 v0, v1, v0, 32 bitop3:0x6c
	v_mov_b32_e32 v184, v100
	v_ashrrev_i32_e32 v2, 31, v0
	v_lshrrev_b32_e32 v2, 26, v2
	v_add_u32_e32 v2, v0, v2
	v_lshlrev_b32_e32 v1, 3, v12
	v_ashrrev_i32_e32 v13, 6, v2
	v_and_b32_e32 v2, 0xc0, v2
	v_and_b32_e32 v1, -16, v1
	v_sub_u32_e32 v0, v0, v2
	s_ashr_i32 s8, s0, 6
	v_add_u32_e32 v1, v13, v1
	v_ashrrev_i16_sdwa v0, v3, sext(v0) dst_sel:DWORD dst_unused:UNUSED_PAD src0_sel:DWORD src1_sel:BYTE_0
	v_and_b32_e32 v3, 3, v13
	s_ashr_i32 s65, s64, 31
	s_ashr_i32 s49, s48, 31
	v_and_or_b32 v3, v1, s1, v3
	s_ashr_i32 s9, s0, 8
	s_lshl_b32 s1, s8, 10
	s_lshl_b64 s[4:5], s[64:65], 20
	s_lshl_b64 s[6:7], s[48:49], 20
	s_add_u32 s66, s36, s6
	v_lshlrev_b32_e32 v4, 5, v12
	v_bfe_i32 v14, v0, 0, 16
	v_lshlrev_b32_e32 v0, 1, v1
	v_lshrrev_b32_e32 v2, 2, v1
	s_addc_u32 s67, s37, s7
	s_add_i32 s2, s1, 0
	v_and_b32_e32 v4, 32, v4
	v_and_b32_e32 v0, 24, v0
	v_and_b32_e32 v2, 4, v2
	s_add_i32 m0, s2, 0x10000
	v_or3_b32 v0, v3, v2, v0
	v_add_lshl_u32 v2, v4, v14, 1
	global_load_lds_dwordx4 v186, s[66:67]
	s_add_i32 m0, s2, 0x12000
	v_mov_b32_e32 v190, v103
	s_add_u32 s6, s66, 0x80000
	global_load_lds_dwordx4 v190, s[66:67]
	s_addc_u32 s7, s67, 0
	s_add_i32 m0, s2, 0x14000
	v_mov_b32_e32 v188, v101
	global_load_lds_dwordx4 v186, s[6:7]
	s_add_i32 m0, s2, 0x16000
	s_add_u32 s68, s46, s4
	s_addc_u32 s69, s47, s5
	s_add_i32 s4, s2, 0x2000
	global_load_lds_dwordx4 v190, s[6:7]
	s_mov_b32 m0, s2
	s_add_u32 s10, s68, 0x80000
	global_load_lds_dwordx4 v184, s[68:69]
	s_mov_b32 m0, s4
	s_addc_u32 s11, s69, 0
	s_add_i32 s5, s2, 0x4000
	global_load_lds_dwordx4 v188, s[68:69]
	s_mov_b32 m0, s5
	s_add_i32 s6, s2, 0x6000
	global_load_lds_dwordx4 v184, s[10:11]
	s_mov_b32 m0, s6
	v_mov_b32_e32 v187, 0
	global_load_lds_dwordx4 v188, s[10:11]
	v_mov_b32_e32 v191, v187
	v_mov_b32_e32 v185, v187
	v_mov_b32_e32 v189, v187
	s_cmp_eq_u32 s9, 1
	s_mov_b32 s7, 0
	v_lshl_add_u64 v[6:7], s[66:67], 0, v[186:187]
	v_lshl_add_u64 v[4:5], s[66:67], 0, v[190:191]
	v_lshl_add_u64 v[0:1], s[68:69], 0, v[184:185]
	s_cselect_b64 s[50:51], -1, 0
	s_cmp_lg_u32 s9, 1
	v_lshl_add_u64 v[2:3], s[68:69], 0, v[188:189]
	s_cbranch_scc1 .LBB0_879
	s_barrier
; #define PG8_STAGE(bufoff, gbase, voff) do { _Pragma("unroll") for (int _i = 0; _i < 2; ++_i) \
;         __builtin_amdgcn_global_load_lds((const unsigned*)((const char*)(gbase) + (voff)[_i]), (LAS unsigned*)(lds + (bufoff) + ldsw + _i * 8192), 16, 0, 0); } while (0)
; #define PG8_WAIT_V(n) asm volatile("s_waitcnt vmcnt(" #n ")" ::: "memory")
; #define PG8_BAR __builtin_amdgcn_s_barrier()
; template <class Epi, class Sched>
; __device__ __forceinline__ void gemm_phase(LAS unsigned char* lds, const int K, const int lda, const int ldb, const Sched& S, const Epi& E) {
;     ...
;     const unsigned ldsw = (unsigned)wid * 1024u;
;     const int aoff = lds_byte(wr * 64 + fr, fq * 8), boff = lds_byte(wc * 32 + fr, fq * 8);
;     ...
;     PG8_STAGE(PG8_SB(1, 0), cB + kstep, voffB); PG8_STAGE(PG8_SA(1, 0), cA + kstep, voffA); PG8_STAGE(PG8_SB(1, 1), cB + hB + kstep, voffB);
;     PG8_WAIT_V(6); PG8_BAR;
.LBB0_879:
	s_mov_b64 s[52:53], 0x80
	s_and_b32 s8, s8, 3
	s_add_i32 m0, s2, 0x18000
	v_lshl_add_u64 v[6:7], v[6:7], 0, s[52:53]
	s_lshl_b32 s12, s9, 13
	s_lshl_b32 s13, s8, 12
	s_waitcnt vmcnt(2)
	s_barrier
	global_load_lds_dwordx4 v[6:7], off
	v_lshl_add_u64 v[4:5], v[4:5], 0, s[52:53]
	s_add_i32 m0, s2, 0x1a000
	s_add_i32 s14, s2, 0x8000
	s_add_i32 s15, s2, 0xa000
	global_load_lds_dwordx4 v[4:5], off
	v_lshl_add_u64 v[0:1], v[0:1], 0, s[52:53]
	s_mov_b32 m0, s14
	s_add_u32 s10, s66, 0x80080
	global_load_lds_dwordx4 v[0:1], off
	v_lshl_add_u64 v[0:1], v[2:3], 0, s[52:53]
	s_mov_b32 m0, s15
	s_addc_u32 s11, s67, 0
	global_load_lds_dwordx4 v[0:1], off
	s_add_i32 m0, s2, 0x1c000
	v_lshl_add_u64 v[0:1], s[10:11], 0, v[186:187]
	global_load_lds_dwordx4 v[0:1], off
	v_lshl_add_u64 v[0:1], s[10:11], 0, v[190:191]
	s_add_i32 m0, s2, 0x1e000
	v_lshrrev_b32_e32 v2, 1, v8
	global_load_lds_dwordx4 v[0:1], off
	v_and_b32_e32 v1, 15, v8
	v_and_b32_e32 v2, 24, v2
	v_and_b32_e32 v3, 48, v8
	v_lshl_or_b32 v216, s9, 6, v1
	v_lshl_or_b32 v1, v1, 6, v3
	v_lshlrev_b32_e32 v3, 2, v8
	v_lshl_or_b32 v218, s8, 5, v2
	v_lshlrev_b32_e32 v2, 15, v12
	v_and_b32_e32 v3, 32, v3
	v_and_b32_e32 v2, 0xffff0000, v2
	v_bitop3_b32 v4, v1, s12, v3 bitop3:0xde
	v_mov_b32_e32 v217, v105
	v_lshl_add_u32 v2, v13, 12, v2
	v_and_b32_e32 v3, 1, v12
	v_lshl_or_b32 v2, v3, 6, v2
	v_mov_b32_e32 v192, v101
	v_lshlrev_b32_e32 v2, 15, v9
	s_cmpk_lt_u32 s0, 0x100
	s_movk_i32 s11, 0xffc0
	v_mov_b32_e32 v1, s0
	v_and_b32_e32 v2, 0xffff0000, v2
	s_cselect_b64 s[54:55], -1, 0
	s_lshl_b32 s8, s8, 2
	v_bfi_b32 v219, s11, v1, v8
	v_lshl_add_u32 v2, v10, 12, v2
	v_and_b32_e32 v3, 1, v9
	v_and_b32_e32 v0, 63, v8
	s_waitcnt vmcnt(6)
	s_add_i32 s8, s8, 0
	v_lshlrev_b32_e32 v1, 4, v219
	v_lshl_or_b32 v2, v3, 6, v2
	s_movk_i32 s10, 0x100
	s_add_i32 s12, s8, 0x20000
	v_cmp_gt_u32_e64 s[8:9], 16, v0
	v_lshlrev_b32_e32 v0, 4, v216
	v_mov_b32_e32 v194, v100
	s_add_i32 s0, 0, 0x10000
	s_add_i32 s23, 0, 0x14000
	v_mbcnt_lo_u32_b32 v2, -1, 0
	v_add_u32_e32 v1, 0, v1
	v_cmp_gt_i32_e64 s[10:11], s10, v219
	s_ashr_i32 s17, s3, 31
	s_ashr_i32 s21, s33, 31
	v_mov_b32_e32 v193, v187
	v_mov_b32_e32 v195, v187
	v_mov_b64_e32 v[196:197], 0x400
	v_mov_b64_e32 v[198:199], 0x3ff
	v_add_u32_e32 v220, s0, v217
	v_add_u32_e32 v221, s23, v217
	v_mov_b32_e32 v222, v104
	v_xor_b32_e32 v246, 64, v222
	v_xor_b32_e32 v247, 64, v220
	v_xor_b32_e32 v248, 64, v221
	v_xor_b32_e32 v249, 64, v217
	v_mbcnt_hi_u32_b32 v223, -1, v2
	v_add_u32_e32 v224, 0x20000, v1
	v_add_u32_e32 v225, s12, v0
	s_barrier
	s_branch .LBB0_882

; #define PG8_STAGE(bufoff, gbase, voff) do { _Pragma("unroll") for (int _i = 0; _i < 2; ++_i) \
;         __builtin_amdgcn_global_load_lds((const unsigned*)((const char*)(gbase) + (voff)[_i]), (LAS unsigned*)(lds + (bufoff) + ldsw + _i * 8192), 16, 0, 0); } while (0)
; #define PG8_LDA(dst, b, h) do { _Pragma("unroll") for (int m = 0; m < 4; ++m) _Pragma("unroll") for (int k = 0; k < 2; ++k) dst[m][k] = *(const LAS bf16x8*)(lds + PG8_SA(b, h) + aoff + m * 2048 + k * 1024); } while (0)
; #define PG8_LDB(dst, b, h) do { _Pragma("unroll") for (int n = 0; n < 2; ++n) _Pragma("unroll") for (int k = 0; k < 2; ++k) dst[n][k] = *(const LAS bf16x8*)(lds + PG8_SB(b, h) + boff + n * 2048 + k * 1024); } while (0)
; #define PG8_MMA(ai, bj, At, Bt) do { __builtin_amdgcn_s_setprio(1); _Pragma("unroll") for (int m = 0; m < 4; ++m) _Pragma("unroll") for (int n = 0; n < 2; ++n) _Pragma("unroll") for (int k = 0; k < 2; ++k) \
;         acc[ai][bj][m][n] = __builtin_amdgcn_mfma_f32_16x16x32_bf16(Bt[n][k], At[m][k], acc[ai][bj][m][n], 0, 0, 0); __builtin_amdgcn_s_setprio(0); } while (0)
; #define PG8_WAIT_V(n) asm volatile("s_waitcnt vmcnt(" #n ")" ::: "memory")
; #define PG8_WAIT_L(n) asm volatile("s_waitcnt lgkmcnt(" #n ")" ::: "memory")
; #define PG8_BAR __builtin_amdgcn_s_barrier()
; #define PG8_SCHED __builtin_amdgcn_sched_barrier(0)
; template <class Epi, class Sched>
; __device__ __forceinline__ void gemm_phase(LAS unsigned char* lds, const int K, const int lda, const int ldb, const Sched& S, const Epi& E) {
;     ...
;             PG8_LDB(B0, 0, 0); PG8_LDB(B1, 0, 1); PG8_SCHED; PG8_LDA(At, 0, 0); PG8_STAGE(PG8_SA(1, 1), a1 + hA, voffA);
;             PG8_WAIT_V(8); PG8_WAIT_L(0); PG8_BAR; PG8_MMA(0, 0, At, B0); PG8_MMA(0, 1, At, B1); PG8_BAR; PG8_SCHED;
;             PG8_LDA(At, 0, 1); PG8_STAGE(PG8_SB(0, 0), b2, voffB); PG8_STAGE(PG8_SB(0, 1), b2 + hB, voffB); PG8_STAGE(PG8_SA(0, 0), a2, voffA);
.LBB0_889:
	ds_read_b128 v[104:107], v220
	ds_read_b128 v[112:115], v247
	ds_read_b128 v[124:127], v220 offset:2048
	ds_read_b128 v[140:143], v247 offset:2048
	ds_read_b128 v[144:147], v221
	ds_read_b128 v[148:151], v248
	ds_read_b128 v[152:155], v221 offset:2048
	ds_read_b128 v[156:159], v248 offset:2048
	s_add_u32 s29, s66, 0xfff80080
	s_addc_u32 s30, s67, -1
	s_cmp_eq_u32 s28, 28
	s_cselect_b32 s71, s18, s30
	s_cselect_b32 s70, s19, s29
	s_cselect_b32 s69, s24, s27
	s_cselect_b32 s68, s25, s26
	v_lshl_add_u64 v[208:209], s[66:67], 0, v[194:195]
	s_add_i32 m0, s2, 0xc000
	ds_read_b128 v[160:163], v222
	ds_read_b128 v[164:167], v246
	ds_read_b128 v[168:171], v222 offset:2048
	ds_read_b128 v[172:175], v246 offset:2048
	ds_read_b128 v[176:179], v222 offset:4096
	ds_read_b128 v[180:183], v246 offset:4096
	ds_read_b128 v[200:203], v222 offset:6144
	ds_read_b128 v[204:207], v246 offset:6144
	global_load_lds_dwordx4 v[208:209], off
	v_lshl_add_u64 v[208:209], s[66:67], 0, v[192:193]
	s_add_i32 m0, s2, 0xe000
	s_nop 0
	global_load_lds_dwordx4 v[208:209], off
	s_waitcnt vmcnt(8)
	s_waitcnt lgkmcnt(0)
	s_barrier
	s_setprio 1
	s_waitcnt lgkmcnt(0)
	v_mfma_f32_16x16x32_bf16 v[136:139], v[104:107], v[160:163], v[136:139]
	v_mfma_f32_16x16x32_bf16 v[132:135], v[124:127], v[160:163], v[132:135]
	v_mfma_f32_16x16x32_bf16 v[116:119], v[104:107], v[168:171], v[116:119]
	v_mfma_f32_16x16x32_bf16 v[108:111], v[124:127], v[168:171], v[108:111]
	v_mfma_f32_16x16x32_bf16 v[92:95], v[104:107], v[176:179], v[92:95]
	v_mfma_f32_16x16x32_bf16 v[88:91], v[124:127], v[176:179], v[88:91]
	v_mfma_f32_16x16x32_bf16 v[76:79], v[104:107], v[200:203], v[76:79]
	v_mfma_f32_16x16x32_bf16 v[72:75], v[124:127], v[200:203], v[72:75]
	v_mfma_f32_16x16x32_bf16 v[136:139], v[112:115], v[164:167], v[136:139]
	v_mfma_f32_16x16x32_bf16 v[132:135], v[140:143], v[164:167], v[132:135]
	v_mfma_f32_16x16x32_bf16 v[116:119], v[112:115], v[172:175], v[116:119]
	v_mfma_f32_16x16x32_bf16 v[108:111], v[140:143], v[172:175], v[108:111]
	v_mfma_f32_16x16x32_bf16 v[92:95], v[112:115], v[180:183], v[92:95]
	v_mfma_f32_16x16x32_bf16 v[88:91], v[140:143], v[180:183], v[88:91]
	v_mfma_f32_16x16x32_bf16 v[76:79], v[112:115], v[204:207], v[76:79]
	v_mfma_f32_16x16x32_bf16 v[72:75], v[140:143], v[204:207], v[72:75]
	s_setprio 0
	s_setprio 1
	v_mfma_f32_16x16x32_bf16 v[128:131], v[144:147], v[160:163], v[128:131]
	v_mfma_f32_16x16x32_bf16 v[120:123], v[152:155], v[160:163], v[120:123]
	v_mfma_f32_16x16x32_bf16 v[100:103], v[144:147], v[168:171], v[100:103]
	v_mfma_f32_16x16x32_bf16 v[96:99], v[152:155], v[168:171], v[96:99]
	v_mfma_f32_16x16x32_bf16 v[84:87], v[144:147], v[176:179], v[84:87]
	v_mfma_f32_16x16x32_bf16 v[80:83], v[152:155], v[176:179], v[80:83]
	v_mfma_f32_16x16x32_bf16 v[68:71], v[144:147], v[200:203], v[68:71]
	v_mfma_f32_16x16x32_bf16 v[64:67], v[152:155], v[200:203], v[64:67]
	v_mfma_f32_16x16x32_bf16 v[128:131], v[148:151], v[164:167], v[128:131]
	v_mfma_f32_16x16x32_bf16 v[120:123], v[156:159], v[164:167], v[120:123]
	v_mfma_f32_16x16x32_bf16 v[100:103], v[148:151], v[172:175], v[100:103]
	v_mfma_f32_16x16x32_bf16 v[96:99], v[156:159], v[172:175], v[96:99]
	v_mfma_f32_16x16x32_bf16 v[84:87], v[148:151], v[180:183], v[84:87]
	v_mfma_f32_16x16x32_bf16 v[80:83], v[156:159], v[180:183], v[80:83]
	v_mfma_f32_16x16x32_bf16 v[68:71], v[148:151], v[204:207], v[68:71]
	v_mfma_f32_16x16x32_bf16 v[64:67], v[156:159], v[204:207], v[64:67]
	s_setprio 0
	s_barrier
	s_add_i32 s29, s0, s1
	v_lshl_add_u64 v[208:209], s[68:69], 0, v[186:187]
	s_mov_b32 m0, s29
	ds_read_b128 v[160:163], v222 offset:16384
	ds_read_b128 v[164:167], v246 offset:16384
	ds_read_b128 v[168:171], v222 offset:18432
	ds_read_b128 v[172:175], v246 offset:18432
	ds_read_b128 v[176:179], v222 offset:20480
	ds_read_b128 v[180:183], v246 offset:20480
	ds_read_b128 v[200:203], v222 offset:22528
	ds_read_b128 v[204:207], v246 offset:22528
	global_load_lds_dwordx4 v[208:209], off
	s_add_i32 m0, s29, 0x2000
	s_add_u32 s30, s68, 0x80000
	v_lshl_add_u64 v[210:211], s[68:69], 0, v[190:191]
	s_addc_u32 s31, s69, 0
	s_add_i32 s29, s23, s1
	global_load_lds_dwordx4 v[210:211], off
	v_lshl_add_u64 v[212:213], s[30:31], 0, v[186:187]
	s_mov_b32 m0, s29
	v_lshl_add_u64 v[214:215], s[70:71], 0, v[188:189]
	global_load_lds_dwordx4 v[212:213], off
	v_lshl_add_u64 v[212:213], s[30:31], 0, v[190:191]
	s_add_i32 m0, s29, 0x2000
	s_nop 0
	global_load_lds_dwordx4 v[212:213], off
	v_lshl_add_u64 v[212:213], s[70:71], 0, v[184:185]
	s_mov_b32 m0, s2
	s_nop 0
	global_load_lds_dwordx4 v[212:213], off
	s_mov_b32 m0, s4
	s_nop 0
	global_load_lds_dwordx4 v[214:215], off
	s_waitcnt vmcnt(8)
	s_waitcnt lgkmcnt(0)
	s_barrier
; #define PG8_STAGE(bufoff, gbase, voff) do { _Pragma("unroll") for (int _i = 0; _i < 2; ++_i) \
;         __builtin_amdgcn_global_load_lds((const unsigned*)((const char*)(gbase) + (voff)[_i]), (LAS unsigned*)(lds + (bufoff) + ldsw + _i * 8192), 16, 0, 0); } while (0)
; #define PG8_LDA(dst, b, h) do { _Pragma("unroll") for (int m = 0; m < 4; ++m) _Pragma("unroll") for (int k = 0; k < 2; ++k) dst[m][k] = *(const LAS bf16x8*)(lds + PG8_SA(b, h) + aoff + m * 2048 + k * 1024); } while (0)
; #define PG8_LDB(dst, b, h) do { _Pragma("unroll") for (int n = 0; n < 2; ++n) _Pragma("unroll") for (int k = 0; k < 2; ++k) dst[n][k] = *(const LAS bf16x8*)(lds + PG8_SB(b, h) + boff + n * 2048 + k * 1024); } while (0)
; #define PG8_MMA(ai, bj, At, Bt) do { __builtin_amdgcn_s_setprio(1); _Pragma("unroll") for (int m = 0; m < 4; ++m) _Pragma("unroll") for (int n = 0; n < 2; ++n) _Pragma("unroll") for (int k = 0; k < 2; ++k) \
;         acc[ai][bj][m][n] = __builtin_amdgcn_mfma_f32_16x16x32_bf16(Bt[n][k], At[m][k], acc[ai][bj][m][n], 0, 0, 0); __builtin_amdgcn_s_setprio(0); } while (0)
; #define PG8_WAIT_V(n) asm volatile("s_waitcnt vmcnt(" #n ")" ::: "memory")
; #define PG8_WAIT_L(n) asm volatile("s_waitcnt lgkmcnt(" #n ")" ::: "memory")
; #define PG8_BAR __builtin_amdgcn_s_barrier()
; #define PG8_SCHED __builtin_amdgcn_sched_barrier(0)
; template <class Epi, class Sched>
; __device__ __forceinline__ void gemm_phase(LAS unsigned char* lds, const int K, const int lda, const int ldb, const Sched& S, const Epi& E) {
;     ...
;             PG8_WAIT_V(8); PG8_WAIT_L(0); PG8_BAR; PG8_MMA(1, 0, At, B0); PG8_MMA(1, 1, At, B1); PG8_BAR; PG8_SCHED;
;             PG8_LDB(B0, 1, 0); PG8_LDB(B1, 1, 1); PG8_SCHED; PG8_LDA(At, 1, 0); PG8_STAGE(PG8_SA(0, 1), a2 + hA, voffA);
;             PG8_WAIT_V(8); PG8_WAIT_L(0); PG8_BAR; PG8_MMA(0, 0, At, B0); PG8_MMA(0, 1, At, B1); PG8_BAR; PG8_SCHED;
	s_setprio 1
	s_waitcnt lgkmcnt(0)
	v_mfma_f32_16x16x32_bf16 v[60:63], v[104:107], v[160:163], v[60:63]
	v_mfma_f32_16x16x32_bf16 v[56:59], v[124:127], v[160:163], v[56:59]
	v_mfma_f32_16x16x32_bf16 v[44:47], v[104:107], v[168:171], v[44:47]
	v_mfma_f32_16x16x32_bf16 v[40:43], v[124:127], v[168:171], v[40:43]
	v_mfma_f32_16x16x32_bf16 v[28:31], v[104:107], v[176:179], v[28:31]
	v_mfma_f32_16x16x32_bf16 v[24:27], v[124:127], v[176:179], v[24:27]
	v_mfma_f32_16x16x32_bf16 v[12:15], v[104:107], v[200:203], v[12:15]
	v_mfma_f32_16x16x32_bf16 v[8:11], v[124:127], v[200:203], v[8:11]
	v_mfma_f32_16x16x32_bf16 v[60:63], v[112:115], v[164:167], v[60:63]
	v_mfma_f32_16x16x32_bf16 v[56:59], v[140:143], v[164:167], v[56:59]
	v_mfma_f32_16x16x32_bf16 v[44:47], v[112:115], v[172:175], v[44:47]
	v_mfma_f32_16x16x32_bf16 v[40:43], v[140:143], v[172:175], v[40:43]
	v_mfma_f32_16x16x32_bf16 v[28:31], v[112:115], v[180:183], v[28:31]
	v_mfma_f32_16x16x32_bf16 v[24:27], v[140:143], v[180:183], v[24:27]
	v_mfma_f32_16x16x32_bf16 v[12:15], v[112:115], v[204:207], v[12:15]
	v_mfma_f32_16x16x32_bf16 v[8:11], v[140:143], v[204:207], v[8:11]
	s_setprio 0
	s_setprio 1
	v_mfma_f32_16x16x32_bf16 v[52:55], v[144:147], v[160:163], v[52:55]
	v_mfma_f32_16x16x32_bf16 v[48:51], v[152:155], v[160:163], v[48:51]
	v_mfma_f32_16x16x32_bf16 v[36:39], v[144:147], v[168:171], v[36:39]
	v_mfma_f32_16x16x32_bf16 v[32:35], v[152:155], v[168:171], v[32:35]
	v_mfma_f32_16x16x32_bf16 v[20:23], v[144:147], v[176:179], v[20:23]
	v_mfma_f32_16x16x32_bf16 v[16:19], v[152:155], v[176:179], v[16:19]
	v_mfma_f32_16x16x32_bf16 v[4:7], v[144:147], v[200:203], v[4:7]
	v_mfma_f32_16x16x32_bf16 v[0:3], v[152:155], v[200:203], v[0:3]
	v_mfma_f32_16x16x32_bf16 v[52:55], v[148:151], v[164:167], v[52:55]
	v_mfma_f32_16x16x32_bf16 v[48:51], v[156:159], v[164:167], v[48:51]
	v_mfma_f32_16x16x32_bf16 v[36:39], v[148:151], v[172:175], v[36:39]
	v_mfma_f32_16x16x32_bf16 v[32:35], v[156:159], v[172:175], v[32:35]
	v_mfma_f32_16x16x32_bf16 v[20:23], v[148:151], v[180:183], v[20:23]
	v_mfma_f32_16x16x32_bf16 v[16:19], v[156:159], v[180:183], v[16:19]
	v_mfma_f32_16x16x32_bf16 v[4:7], v[148:151], v[204:207], v[4:7]
	v_mfma_f32_16x16x32_bf16 v[0:3], v[156:159], v[204:207], v[0:3]
	s_setprio 0
	s_barrier
	s_add_i32 s29, 0, 0x18000
	s_add_i32 s34, 0, 0x1c000
	v_add_u32_e32 v140, s29, v217
	v_add_u32_e32 v250, s29, v249
	v_add_u32_e32 v156, s34, v217
	v_add_u32_e32 v251, s34, v249
	ds_read_b128 v[104:107], v140
	ds_read_b128 v[112:115], v250
	ds_read_b128 v[124:127], v140 offset:2048
	ds_read_b128 v[140:143], v250 offset:2048
	ds_read_b128 v[144:147], v156
	ds_read_b128 v[148:151], v251
	ds_read_b128 v[152:155], v156 offset:2048
	ds_read_b128 v[156:159], v251 offset:2048
	s_add_u32 s30, s70, 0x80000
	s_addc_u32 s31, s71, 0
	s_mov_b32 m0, s5
	v_lshl_add_u64 v[226:227], s[30:31], 0, v[184:185]
	ds_read_b128 v[160:163], v222 offset:32768
	ds_read_b128 v[164:167], v246 offset:32768
	ds_read_b128 v[168:171], v222 offset:34816
	ds_read_b128 v[172:175], v246 offset:34816
	ds_read_b128 v[176:179], v222 offset:36864
	ds_read_b128 v[180:183], v246 offset:36864
	ds_read_b128 v[200:203], v222 offset:38912
	ds_read_b128 v[204:207], v246 offset:38912
	global_load_lds_dwordx4 v[226:227], off
	v_lshl_add_u64 v[226:227], s[30:31], 0, v[188:189]
	s_mov_b32 m0, s6
	s_nop 0
	global_load_lds_dwordx4 v[226:227], off
	s_waitcnt vmcnt(8)
	s_waitcnt lgkmcnt(0)
	s_barrier
	s_setprio 1
	s_waitcnt lgkmcnt(0)
	v_mfma_f32_16x16x32_bf16 v[136:139], v[104:107], v[160:163], v[136:139]
	v_mfma_f32_16x16x32_bf16 v[132:135], v[124:127], v[160:163], v[132:135]
	v_mfma_f32_16x16x32_bf16 v[116:119], v[104:107], v[168:171], v[116:119]
	v_mfma_f32_16x16x32_bf16 v[108:111], v[124:127], v[168:171], v[108:111]
	v_mfma_f32_16x16x32_bf16 v[92:95], v[104:107], v[176:179], v[92:95]
	v_mfma_f32_16x16x32_bf16 v[88:91], v[124:127], v[176:179], v[88:91]
	v_mfma_f32_16x16x32_bf16 v[76:79], v[104:107], v[200:203], v[76:79]
	v_mfma_f32_16x16x32_bf16 v[72:75], v[124:127], v[200:203], v[72:75]
	v_mfma_f32_16x16x32_bf16 v[136:139], v[112:115], v[164:167], v[136:139]
	v_mfma_f32_16x16x32_bf16 v[132:135], v[140:143], v[164:167], v[132:135]
	v_mfma_f32_16x16x32_bf16 v[116:119], v[112:115], v[172:175], v[116:119]
	v_mfma_f32_16x16x32_bf16 v[108:111], v[140:143], v[172:175], v[108:111]
	v_mfma_f32_16x16x32_bf16 v[92:95], v[112:115], v[180:183], v[92:95]
	v_mfma_f32_16x16x32_bf16 v[88:91], v[140:143], v[180:183], v[88:91]
	v_mfma_f32_16x16x32_bf16 v[76:79], v[112:115], v[204:207], v[76:79]
	v_mfma_f32_16x16x32_bf16 v[72:75], v[140:143], v[204:207], v[72:75]
	s_setprio 0
	s_setprio 1
	v_mfma_f32_16x16x32_bf16 v[128:131], v[144:147], v[160:163], v[128:131]
	v_mfma_f32_16x16x32_bf16 v[120:123], v[152:155], v[160:163], v[120:123]
	v_mfma_f32_16x16x32_bf16 v[100:103], v[144:147], v[168:171], v[100:103]
	v_mfma_f32_16x16x32_bf16 v[96:99], v[152:155], v[168:171], v[96:99]
	v_mfma_f32_16x16x32_bf16 v[84:87], v[144:147], v[176:179], v[84:87]
	v_mfma_f32_16x16x32_bf16 v[80:83], v[152:155], v[176:179], v[80:83]
	v_mfma_f32_16x16x32_bf16 v[68:71], v[144:147], v[200:203], v[68:71]
	v_mfma_f32_16x16x32_bf16 v[64:67], v[152:155], v[200:203], v[64:67]
	v_mfma_f32_16x16x32_bf16 v[128:131], v[148:151], v[164:167], v[128:131]
	v_mfma_f32_16x16x32_bf16 v[120:123], v[156:159], v[164:167], v[120:123]
	v_mfma_f32_16x16x32_bf16 v[100:103], v[148:151], v[172:175], v[100:103]
	v_mfma_f32_16x16x32_bf16 v[96:99], v[156:159], v[172:175], v[96:99]
	v_mfma_f32_16x16x32_bf16 v[84:87], v[148:151], v[180:183], v[84:87]
	v_mfma_f32_16x16x32_bf16 v[80:83], v[156:159], v[180:183], v[80:83]
	v_mfma_f32_16x16x32_bf16 v[68:71], v[148:151], v[204:207], v[68:71]
	v_mfma_f32_16x16x32_bf16 v[64:67], v[156:159], v[204:207], v[64:67]
	s_setprio 0
	s_barrier
; #define PG8_STAGE(bufoff, gbase, voff) do { _Pragma("unroll") for (int _i = 0; _i < 2; ++_i) \
;         __builtin_amdgcn_global_load_lds((const unsigned*)((const char*)(gbase) + (voff)[_i]), (LAS unsigned*)(lds + (bufoff) + ldsw + _i * 8192), 16, 0, 0); } while (0)
; #define PG8_LDA(dst, b, h) do { _Pragma("unroll") for (int m = 0; m < 4; ++m) _Pragma("unroll") for (int k = 0; k < 2; ++k) dst[m][k] = *(const LAS bf16x8*)(lds + PG8_SA(b, h) + aoff + m * 2048 + k * 1024); } while (0)
; #define PG8_MMA(ai, bj, At, Bt) do { __builtin_amdgcn_s_setprio(1); _Pragma("unroll") for (int m = 0; m < 4; ++m) _Pragma("unroll") for (int n = 0; n < 2; ++n) _Pragma("unroll") for (int k = 0; k < 2; ++k) \
;         acc[ai][bj][m][n] = __builtin_amdgcn_mfma_f32_16x16x32_bf16(Bt[n][k], At[m][k], acc[ai][bj][m][n], 0, 0, 0); __builtin_amdgcn_s_setprio(0); } while (0)
; #define PG8_WAIT_V(n) asm volatile("s_waitcnt vmcnt(" #n ")" ::: "memory")
; #define PG8_WAIT_L(n) asm volatile("s_waitcnt lgkmcnt(" #n ")" ::: "memory")
; #define PG8_BAR __builtin_amdgcn_s_barrier()
; #define PG8_SCHED __builtin_amdgcn_sched_barrier(0)
; template <class Epi, class Sched>
; __device__ __forceinline__ void gemm_phase(LAS unsigned char* lds, const int K, const int lda, const int ldb, const Sched& S, const Epi& E) {
;     ...
;             PG8_LDA(At, 1, 1); PG8_STAGE(PG8_SB(1, 0), b3, voffB); PG8_STAGE(PG8_SB(1, 1), b3 + hB, voffB); PG8_STAGE(PG8_SA(1, 0), a3, voffA);
;             PG8_WAIT_V(8); PG8_WAIT_L(0); PG8_BAR; PG8_MMA(1, 0, At, B0); PG8_MMA(1, 1, At, B1); PG8_BAR; PG8_SCHED;
;         }
	s_add_i32 s29, s29, s1
	v_lshl_add_u64 v[208:209], v[208:209], 0, s[52:53]
	s_mov_b32 m0, s29
	ds_read_b128 v[160:163], v222 offset:49152
	ds_read_b128 v[164:167], v246 offset:49152
	ds_read_b128 v[168:171], v222 offset:51200
	ds_read_b128 v[172:175], v246 offset:51200
	ds_read_b128 v[176:179], v222 offset:53248
	ds_read_b128 v[180:183], v246 offset:53248
	ds_read_b128 v[200:203], v222 offset:55296
	ds_read_b128 v[204:207], v246 offset:55296
	global_load_lds_dwordx4 v[208:209], off
	s_add_i32 m0, s29, 0x2000
	s_add_u32 s30, s68, 0x80080
	v_lshl_add_u64 v[208:209], v[210:211], 0, s[52:53]
	s_addc_u32 s31, s69, 0
	s_add_i32 s29, s34, s1
	global_load_lds_dwordx4 v[208:209], off
	v_lshl_add_u64 v[208:209], s[30:31], 0, v[186:187]
	s_mov_b32 m0, s29
	s_nop 0
	global_load_lds_dwordx4 v[208:209], off
	v_lshl_add_u64 v[208:209], s[30:31], 0, v[190:191]
	s_add_i32 m0, s29, 0x2000
	s_nop 0
	global_load_lds_dwordx4 v[208:209], off
	v_lshl_add_u64 v[208:209], v[212:213], 0, s[52:53]
	s_mov_b32 m0, s14
	s_nop 0
	global_load_lds_dwordx4 v[208:209], off
	v_lshl_add_u64 v[208:209], v[214:215], 0, s[52:53]
	s_mov_b32 m0, s15
	s_nop 0
	global_load_lds_dwordx4 v[208:209], off
	s_waitcnt vmcnt(8)
	s_waitcnt lgkmcnt(0)
	s_barrier
	s_setprio 1
	s_waitcnt lgkmcnt(0)
	v_mfma_f32_16x16x32_bf16 v[60:63], v[104:107], v[160:163], v[60:63]
	v_mfma_f32_16x16x32_bf16 v[56:59], v[124:127], v[160:163], v[56:59]
	v_mfma_f32_16x16x32_bf16 v[44:47], v[104:107], v[168:171], v[44:47]
	v_mfma_f32_16x16x32_bf16 v[40:43], v[124:127], v[168:171], v[40:43]
	v_mfma_f32_16x16x32_bf16 v[28:31], v[104:107], v[176:179], v[28:31]
	v_mfma_f32_16x16x32_bf16 v[24:27], v[124:127], v[176:179], v[24:27]
	v_mfma_f32_16x16x32_bf16 v[12:15], v[104:107], v[200:203], v[12:15]
	v_mfma_f32_16x16x32_bf16 v[8:11], v[124:127], v[200:203], v[8:11]
	v_mfma_f32_16x16x32_bf16 v[60:63], v[112:115], v[164:167], v[60:63]
	v_mfma_f32_16x16x32_bf16 v[56:59], v[140:143], v[164:167], v[56:59]
	v_mfma_f32_16x16x32_bf16 v[44:47], v[112:115], v[172:175], v[44:47]
	v_mfma_f32_16x16x32_bf16 v[40:43], v[140:143], v[172:175], v[40:43]
	v_mfma_f32_16x16x32_bf16 v[28:31], v[112:115], v[180:183], v[28:31]
	v_mfma_f32_16x16x32_bf16 v[24:27], v[140:143], v[180:183], v[24:27]
	v_mfma_f32_16x16x32_bf16 v[12:15], v[112:115], v[204:207], v[12:15]
	v_mfma_f32_16x16x32_bf16 v[8:11], v[140:143], v[204:207], v[8:11]
	s_setprio 0
	s_setprio 1
	v_mfma_f32_16x16x32_bf16 v[52:55], v[144:147], v[160:163], v[52:55]
	v_mfma_f32_16x16x32_bf16 v[48:51], v[152:155], v[160:163], v[48:51]
	v_mfma_f32_16x16x32_bf16 v[36:39], v[144:147], v[168:171], v[36:39]
	v_mfma_f32_16x16x32_bf16 v[32:35], v[152:155], v[168:171], v[32:35]
	v_mfma_f32_16x16x32_bf16 v[20:23], v[144:147], v[176:179], v[20:23]
	v_mfma_f32_16x16x32_bf16 v[16:19], v[152:155], v[176:179], v[16:19]
	v_mfma_f32_16x16x32_bf16 v[4:7], v[144:147], v[200:203], v[4:7]
	v_mfma_f32_16x16x32_bf16 v[0:3], v[152:155], v[200:203], v[0:3]
	v_mfma_f32_16x16x32_bf16 v[52:55], v[148:151], v[164:167], v[52:55]
	v_mfma_f32_16x16x32_bf16 v[48:51], v[156:159], v[164:167], v[48:51]
	v_mfma_f32_16x16x32_bf16 v[36:39], v[148:151], v[172:175], v[36:39]
	v_mfma_f32_16x16x32_bf16 v[32:35], v[156:159], v[172:175], v[32:35]
	v_mfma_f32_16x16x32_bf16 v[20:23], v[148:151], v[180:183], v[20:23]
	v_mfma_f32_16x16x32_bf16 v[16:19], v[156:159], v[180:183], v[16:19]
	v_mfma_f32_16x16x32_bf16 v[4:7], v[148:151], v[204:207], v[4:7]
	v_mfma_f32_16x16x32_bf16 v[0:3], v[156:159], v[204:207], v[0:3]
	s_setprio 0
	s_barrier
	s_add_i32 s28, s28, 2
	s_add_u32 s26, s26, 0x100
	s_addc_u32 s27, s27, 0
	s_add_u32 s66, s66, 0x100
	s_addc_u32 s67, s67, 0
	s_cmp_gt_u32 s28, 29
	s_cbranch_scc0 .LBB0_889
	s_and_b64 vcc, exec, s[54:55]
	s_cbranch_vccz .LBB0_892
	s_barrier

; #define PG8_STAGE(bufoff, gbase, voff) do { _Pragma("unroll") for (int _i = 0; _i < 2; ++_i) \
;         __builtin_amdgcn_global_load_lds((const unsigned*)((const char*)(gbase) + (voff)[_i]), (LAS unsigned*)(lds + (bufoff) + ldsw + _i * 8192), 16, 0, 0); } while (0)
; #define PG8_WAIT_V(n) asm volatile("s_waitcnt vmcnt(" #n ")" ::: "memory")
; #define PG8_BAR __builtin_amdgcn_s_barrier()
; template <class Epi, class Sched>
; __device__ __forceinline__ void gemm_phase(LAS unsigned char* lds, const int K, const int lda, const int ldb, const Sched& S, const Epi& E) {
;     ...
;     for (int i = 0; i < 2; ++i) { int R, C; stage_rc(tid * 16 + i * 8192, R, C); const int Rb = (R & ~31) + perm32(R & 31);
;         voffA[i] = (unsigned)(R * lda + C) * 2u; voffB[i] = (unsigned)(Rb * ldb + C) * 2u; }
;     const size_t kstep = (size_t)(BK * 2);
;     const size_t hA = (size_t)HALF * lda * 2, hB = (size_t)HALF * ldb * 2;
;     const unsigned ldsw = (unsigned)wid * 1024u;
;     const int aoff = lds_byte(wr * 64 + fr, fq * 8), boff = lds_byte(wc * 32 + fr, fq * 8);
;     ...
;     const char* cA = S.aptr(cur); const char* cB = S.bptr(cur);
;     PG8_STAGE(PG8_SB(0, 0), cB, voffB); PG8_STAGE(PG8_SB(0, 1), cB + hB, voffB); PG8_STAGE(PG8_SA(0, 0), cA, voffA); PG8_STAGE(PG8_SA(0, 1), cA + hA, voffA);
;     if (wr == 1) PG8_BAR;
;     PG8_WAIT_V(2); PG8_BAR;
.LBB0_1359:
	v_readlane_b32 s4, v255, 24
	v_readlane_b32 s5, v255, 25
	s_and_b64 vcc, exec, s[4:5]
	s_cbranch_vccnz .LBB0_1397
	v_ashrrev_i32_e32 v1, 31, v8
	v_lshrrev_b32_e32 v1, 26, v1
	v_add_u32_e32 v1, v8, v1
	v_ashrrev_i32_e32 v9, 6, v1
	v_bfe_i32 v1, v8, 27, 1
	v_lshlrev_b32_e32 v0, 4, v8
	v_lshrrev_b32_e32 v1, 22, v1
	v_add_u32_e32 v1, v0, v1
	v_and_b32_e32 v1, 0xfffffc00, v1
	v_sub_u32_e32 v1, v0, v1
	v_lshrrev_b32_e32 v2, 4, v1
	v_bitop3_b32 v1, v2, v1, 32 bitop3:0x6c
	v_ashrrev_i32_e32 v3, 31, v1
	v_lshrrev_b32_e32 v3, 26, v3
	v_add_u32_e32 v3, v1, v3
	v_lshlrev_b32_e32 v2, 3, v9
	v_ashrrev_i32_e32 v10, 6, v3
	v_and_b32_e32 v3, 0xc0, v3
	v_and_b32_e32 v2, -16, v2
	v_sub_u32_e32 v1, v1, v3
	v_mov_b32_e32 v3, 1
	v_add_u32_e32 v2, v10, v2
	v_ashrrev_i16_sdwa v1, v3, sext(v1) dst_sel:DWORD dst_unused:UNUSED_PAD src0_sel:DWORD src1_sel:BYTE_0
	v_lshlrev_b32_e32 v4, 5, v9
	v_bfe_i32 v11, v1, 0, 16
	v_lshlrev_b32_e32 v1, 1, v2
	v_lshrrev_b32_e32 v5, 2, v2
	v_and_b32_e32 v6, 3, v10
	s_mov_b32 s1, 0xfffe0
	v_and_b32_e32 v4, 32, v4
	v_and_b32_e32 v1, 24, v1
	v_and_b32_e32 v5, 4, v5
	v_and_or_b32 v6, v2, s1, v6
	v_or3_b32 v1, v6, v5, v1
	v_add_lshl_u32 v4, v4, v11, 1
	v_add_u32_e32 v0, 0x2000, v0
	v_and_b32_e32 v106, 63, v254
	v_lshrrev_b32_e32 v107, 6, v254
	v_lshrrev_b32_e32 v108, 3, v106
	v_lshl_add_u32 v109, v107, 3, v108
	v_and_b32_e32 v110, 1, v107
	v_bfe_u32 v111, v106, 4, 2
	v_lshl_add_u32 v111, v110, 2, v111
	v_and_b32_e32 v101, 7, v106
	v_xor_b32_e32 v111, v101, v111
	v_lshlrev_b32_e32 v111, 4, v111
	v_lshl_add_u32 v100, v109, 12, v111
	v_add_u32_e32 v101, 0x40000, v100
	v_lshrrev_b32_e32 v109, 5, v106
	v_lshlrev_b32_e32 v109, 3, v109
	v_lshl_add_u32 v109, v110, 4, v109
	v_bfe_u32 v110, v107, 1, 1
	v_lshl_add_u32 v109, v110, 2, v109
	v_and_b32_e32 v110, 3, v108
	v_add_u32_e32 v109, v109, v110
	v_lshrrev_b32_e32 v110, 2, v107
	v_lshl_add_u32 v109, v110, 5, v109
	v_lshl_add_u32 v102, v109, 12, v111
	v_add_u32_e32 v103, 0x40000, v102
	v_and_b32_e32 v106, 15, v254
	v_bfe_u32 v108, v254, 4, 2
	v_bfe_u32 v109, v254, 1, 3
	v_xor_b32_e32 v108, v108, v109
	v_lshlrev_b32_e32 v108, 4, v108
	v_lshl_add_u32 v108, v106, 7, v108
	v_lshrrev_b32_e32 v109, 8, v254
	v_lshl_add_u32 v104, v109, 13, v108
	v_and_b32_e32 v109, 3, v107
	v_lshl_add_u32 v105, v109, 12, v108
	v_mov_b32_e32 v186, v102
	v_ashrrev_i32_e32 v1, 31, v0
	v_lshrrev_b32_e32 v1, 22, v1
	v_add_u32_e32 v1, v0, v1
	v_ashrrev_i32_e32 v12, 10, v1
	v_mul_i32_i24_e32 v1, 0x400, v12
	v_sub_u32_e32 v0, v0, v1
	v_lshrrev_b32_e32 v1, 4, v0
	v_bitop3_b32 v0, v1, v0, 32 bitop3:0x6c
	v_mov_b32_e32 v184, v100
	v_ashrrev_i32_e32 v2, 31, v0
	v_lshrrev_b32_e32 v2, 26, v2
	v_add_u32_e32 v2, v0, v2
	v_lshlrev_b32_e32 v1, 3, v12
	v_ashrrev_i32_e32 v13, 6, v2
	v_and_b32_e32 v2, 0xc0, v2
	v_and_b32_e32 v1, -16, v1
	v_sub_u32_e32 v0, v0, v2
	s_ashr_i32 s8, s0, 6
	v_add_u32_e32 v1, v13, v1
	v_ashrrev_i16_sdwa v0, v3, sext(v0) dst_sel:DWORD dst_unused:UNUSED_PAD src0_sel:DWORD src1_sel:BYTE_0
	v_and_b32_e32 v3, 3, v13
	s_ashr_i32 s51, s50, 31
	s_ashr_i32 s17, s16, 31
	v_and_or_b32 v3, v1, s1, v3
	s_ashr_i32 s9, s0, 8
	s_lshl_b32 s1, s8, 10
	s_lshl_b64 s[4:5], s[50:51], 20
	s_lshl_b64 s[6:7], s[16:17], 20
	s_add_u32 s52, s36, s6
	v_lshlrev_b32_e32 v4, 5, v12
	v_bfe_i32 v14, v0, 0, 16
	v_lshlrev_b32_e32 v0, 1, v1
	v_lshrrev_b32_e32 v2, 2, v1
	s_addc_u32 s53, s37, s7
	s_add_i32 s2, s1, 0
	v_and_b32_e32 v4, 32, v4
	v_and_b32_e32 v0, 24, v0
	v_and_b32_e32 v2, 4, v2
	s_add_i32 m0, s2, 0x10000
	v_or3_b32 v0, v3, v2, v0
	v_add_lshl_u32 v2, v4, v14, 1
	global_load_lds_dwordx4 v186, s[52:53]
	s_add_i32 m0, s2, 0x12000
	v_mov_b32_e32 v190, v103
	s_add_u32 s6, s52, 0x80000
	global_load_lds_dwordx4 v190, s[52:53]
	s_addc_u32 s7, s53, 0
	s_add_i32 m0, s2, 0x14000
	v_mov_b32_e32 v188, v101
	global_load_lds_dwordx4 v186, s[6:7]
	s_add_i32 m0, s2, 0x16000
	s_add_u32 s54, s28, s4
	s_addc_u32 s55, s29, s5
	s_add_i32 s4, s2, 0x2000
	global_load_lds_dwordx4 v190, s[6:7]
	s_mov_b32 m0, s2
	s_add_u32 s10, s54, 0x80000
	global_load_lds_dwordx4 v184, s[54:55]
	s_mov_b32 m0, s4
	s_addc_u32 s11, s55, 0
	s_add_i32 s5, s2, 0x4000
	global_load_lds_dwordx4 v188, s[54:55]
	s_mov_b32 m0, s5
	s_add_i32 s6, s2, 0x6000
	global_load_lds_dwordx4 v184, s[10:11]
	s_mov_b32 m0, s6
	v_mov_b32_e32 v187, 0
	global_load_lds_dwordx4 v188, s[10:11]
	v_mov_b32_e32 v191, v187
	v_mov_b32_e32 v185, v187
	v_mov_b32_e32 v189, v187
	s_cmp_eq_u32 s9, 1
	s_mov_b32 s7, 0
	v_lshl_add_u64 v[6:7], s[52:53], 0, v[186:187]
	v_lshl_add_u64 v[4:5], s[52:53], 0, v[190:191]
	v_lshl_add_u64 v[0:1], s[54:55], 0, v[184:185]
	s_cselect_b64 s[18:19], -1, 0
	s_cmp_lg_u32 s9, 1
	v_lshl_add_u64 v[2:3], s[54:55], 0, v[188:189]
	s_cbranch_scc1 .LBB0_1362
	s_barrier
; #define PG8_STAGE(bufoff, gbase, voff) do { _Pragma("unroll") for (int _i = 0; _i < 2; ++_i) \
;         __builtin_amdgcn_global_load_lds((const unsigned*)((const char*)(gbase) + (voff)[_i]), (LAS unsigned*)(lds + (bufoff) + ldsw + _i * 8192), 16, 0, 0); } while (0)
; #define PG8_WAIT_V(n) asm volatile("s_waitcnt vmcnt(" #n ")" ::: "memory")
; #define PG8_BAR __builtin_amdgcn_s_barrier()
; template <class Epi, class Sched>
; __device__ __forceinline__ void gemm_phase(LAS unsigned char* lds, const int K, const int lda, const int ldb, const Sched& S, const Epi& E) {
;     ...
;     for (int i = 0; i < 2; ++i) { int R, C; stage_rc(tid * 16 + i * 8192, R, C); const int Rb = (R & ~31) + perm32(R & 31);
;         voffA[i] = (unsigned)(R * lda + C) * 2u; voffB[i] = (unsigned)(Rb * ldb + C) * 2u; }
;     const size_t kstep = (size_t)(BK * 2);
;     const size_t hA = (size_t)HALF * lda * 2, hB = (size_t)HALF * ldb * 2;
;     const unsigned ldsw = (unsigned)wid * 1024u;
;     const int aoff = lds_byte(wr * 64 + fr, fq * 8), boff = lds_byte(wc * 32 + fr, fq * 8);
;     ...
;     Unit cur, nxt; int ui = 0;
;     if (!S.next(0, cur)) return;
;     f32x4 acc[2][2][4][2];
; #pragma unroll
;     for (int a = 0; a < 2; ++a)
; #pragma unroll
;         for (int b = 0; b < 2; ++b)
; #pragma unroll
;             for (int m = 0; m < 4; ++m)
; #pragma unroll
;                 for (int n = 0; n < 2; ++n) acc[a][b][m][n] = (f32x4){0.f, 0.f, 0.f, 0.f};
;     bf16x8 At[4][2], B0[2][2], B1[2][2];
;     const char* cA = S.aptr(cur); const char* cB = S.bptr(cur);
;     PG8_STAGE(PG8_SB(0, 0), cB, voffB); PG8_STAGE(PG8_SB(0, 1), cB + hB, voffB); PG8_STAGE(PG8_SA(0, 0), cA, voffA); PG8_STAGE(PG8_SA(0, 1), cA + hA, voffA);
;     if (wr == 1) PG8_BAR;
;     PG8_WAIT_V(2); PG8_BAR;
;     PG8_STAGE(PG8_SB(1, 0), cB + kstep, voffB); PG8_STAGE(PG8_SA(1, 0), cA + kstep, voffA); PG8_STAGE(PG8_SB(1, 1), cB + hB + kstep, voffB);
;     PG8_WAIT_V(6); PG8_BAR;
;     for (;;) {
.LBB0_1362:
	s_mov_b64 s[20:21], 0x80
	s_and_b32 s8, s8, 3
	s_add_i32 m0, s2, 0x18000
	v_lshl_add_u64 v[6:7], v[6:7], 0, s[20:21]
	s_lshl_b32 s12, s9, 13
	s_lshl_b32 s13, s8, 12
	s_waitcnt vmcnt(2)
	s_barrier
	global_load_lds_dwordx4 v[6:7], off
	v_lshl_add_u64 v[4:5], v[4:5], 0, s[20:21]
	s_add_i32 m0, s2, 0x1a000
	s_add_i32 s14, s2, 0x8000
	s_add_i32 s15, s2, 0xa000
	global_load_lds_dwordx4 v[4:5], off
	v_lshl_add_u64 v[0:1], v[0:1], 0, s[20:21]
	s_mov_b32 m0, s14
	s_add_u32 s10, s52, 0x80080
	global_load_lds_dwordx4 v[0:1], off
	v_lshl_add_u64 v[0:1], v[2:3], 0, s[20:21]
	s_mov_b32 m0, s15
	s_addc_u32 s11, s53, 0
	global_load_lds_dwordx4 v[0:1], off
	s_add_i32 m0, s2, 0x1c000
	v_lshl_add_u64 v[0:1], s[10:11], 0, v[186:187]
	global_load_lds_dwordx4 v[0:1], off
	v_lshl_add_u64 v[0:1], s[10:11], 0, v[190:191]
	s_add_i32 m0, s2, 0x1e000
	v_lshrrev_b32_e32 v2, 1, v8
	global_load_lds_dwordx4 v[0:1], off
	v_and_b32_e32 v1, 15, v8
	v_and_b32_e32 v2, 24, v2
	v_and_b32_e32 v3, 48, v8
	v_lshl_or_b32 v216, s9, 6, v1
	v_lshl_or_b32 v1, v1, 6, v3
	v_lshlrev_b32_e32 v3, 2, v8
	v_lshl_or_b32 v218, s8, 5, v2
	v_lshlrev_b32_e32 v2, 15, v12
	v_and_b32_e32 v3, 32, v3
	v_and_b32_e32 v2, 0xffff0000, v2
	v_bitop3_b32 v4, v1, s12, v3 bitop3:0xde
	v_mov_b32_e32 v217, v105
	v_lshl_add_u32 v2, v13, 12, v2
	v_and_b32_e32 v3, 1, v12
	v_lshl_or_b32 v2, v3, 6, v2
	v_mov_b32_e32 v192, v101
	v_lshlrev_b32_e32 v2, 15, v9
	s_cmpk_lt_u32 s0, 0x100
	s_movk_i32 s11, 0xffc0
	v_mov_b32_e32 v1, s0
	v_and_b32_e32 v2, 0xffff0000, v2
	s_cselect_b64 s[22:23], -1, 0
	s_lshl_b32 s8, s8, 2
	v_bfi_b32 v219, s11, v1, v8
	v_lshl_add_u32 v2, v10, 12, v2
	v_and_b32_e32 v3, 1, v9
	v_and_b32_e32 v0, 63, v8
	s_waitcnt vmcnt(6)
	s_add_i32 s8, s8, 0
	v_lshlrev_b32_e32 v1, 4, v219
	v_lshl_or_b32 v2, v3, 6, v2
	s_movk_i32 s10, 0x100
	s_add_i32 s12, s8, 0x20000
	v_cmp_gt_u32_e64 s[8:9], 16, v0
	v_lshlrev_b32_e32 v0, 4, v216
	v_mov_b32_e32 v194, v100
	s_add_i32 s0, 0, 0x10000
	s_add_i32 s34, 0, 0x14000
	v_mbcnt_lo_u32_b32 v2, -1, 0
	v_add_u32_e32 v1, 0, v1
	v_cmp_gt_i32_e64 s[10:11], s10, v219
	s_ashr_i32 s30, s3, 31
	s_ashr_i32 s31, s33, 31
	v_mov_b32_e32 v193, v187
	v_mov_b32_e32 v195, v187
	v_mov_b64_e32 v[196:197], 0x400
	v_mov_b64_e32 v[198:199], 0x3ff
	v_add_u32_e32 v220, s0, v217
	v_add_u32_e32 v221, s34, v217
	v_mov_b32_e32 v222, v104
	v_xor_b32_e32 v246, 64, v222
	v_xor_b32_e32 v247, 64, v220
	v_xor_b32_e32 v248, 64, v221
	v_xor_b32_e32 v249, 64, v217
	v_mbcnt_hi_u32_b32 v223, -1, v2
	v_add_u32_e32 v224, 0x20000, v1
	v_add_u32_e32 v225, s12, v0
	s_barrier
	s_branch .LBB0_1365

; #define PG8_STAGE(bufoff, gbase, voff) do { _Pragma("unroll") for (int _i = 0; _i < 2; ++_i) \
;         __builtin_amdgcn_global_load_lds((const unsigned*)((const char*)(gbase) + (voff)[_i]), (LAS unsigned*)(lds + (bufoff) + ldsw + _i * 8192), 16, 0, 0); } while (0)
; #define PG8_LDA(dst, b, h) do { _Pragma("unroll") for (int m = 0; m < 4; ++m) _Pragma("unroll") for (int k = 0; k < 2; ++k) dst[m][k] = *(const LAS bf16x8*)(lds + PG8_SA(b, h) + aoff + m * 2048 + k * 1024); } while (0)
; #define PG8_LDB(dst, b, h) do { _Pragma("unroll") for (int n = 0; n < 2; ++n) _Pragma("unroll") for (int k = 0; k < 2; ++k) dst[n][k] = *(const LAS bf16x8*)(lds + PG8_SB(b, h) + boff + n * 2048 + k * 1024); } while (0)
; #define PG8_MMA(ai, bj, At, Bt) do { __builtin_amdgcn_s_setprio(1); _Pragma("unroll") for (int m = 0; m < 4; ++m) _Pragma("unroll") for (int n = 0; n < 2; ++n) _Pragma("unroll") for (int k = 0; k < 2; ++k) \
;         acc[ai][bj][m][n] = __builtin_amdgcn_mfma_f32_16x16x32_bf16(Bt[n][k], At[m][k], acc[ai][bj][m][n], 0, 0, 0); __builtin_amdgcn_s_setprio(0); } while (0)
; #define PG8_WAIT_V(n) asm volatile("s_waitcnt vmcnt(" #n ")" ::: "memory")
; #define PG8_WAIT_L(n) asm volatile("s_waitcnt lgkmcnt(" #n ")" ::: "memory")
; #define PG8_BAR __builtin_amdgcn_s_barrier()
; #define PG8_SCHED __builtin_amdgcn_sched_barrier(0)
; template <class Epi, class Sched>
; __device__ __forceinline__ void gemm_phase(LAS unsigned char* lds, const int K, const int lda, const int ldb, const Sched& S, const Epi& E) {
;     ...
;         for (int t = 0; t < nt; t += 2) {
;             const bool last = (t == nt - 2);
;             const char* a1 = cA + (size_t)(t + 1) * kstep;
;             const char* a2 = last ? nA : cA + (size_t)(t + 2) * kstep; const char* b2 = last ? nB : cB + (size_t)(t + 2) * kstep;
;             const char* a3 = a2 + kstep; const char* b3 = b2 + kstep;
;             PG8_LDB(B0, 0, 0); PG8_LDB(B1, 0, 1); PG8_SCHED; PG8_LDA(At, 0, 0); PG8_STAGE(PG8_SA(1, 1), a1 + hA, voffA);
;             PG8_WAIT_V(8); PG8_WAIT_L(0); PG8_BAR; PG8_MMA(0, 0, At, B0); PG8_MMA(0, 1, At, B1); PG8_BAR; PG8_SCHED;
;             PG8_LDA(At, 0, 1); PG8_STAGE(PG8_SB(0, 0), b2, voffB); PG8_STAGE(PG8_SB(0, 1), b2 + hB, voffB); PG8_STAGE(PG8_SA(0, 0), a2, voffA);
;             PG8_WAIT_V(8); PG8_WAIT_L(0); PG8_BAR; PG8_MMA(1, 0, At, B0); PG8_MMA(1, 1, At, B1); PG8_BAR; PG8_SCHED;
.LBB0_1372:
	ds_read_b128 v[104:107], v220
	ds_read_b128 v[112:115], v247
	ds_read_b128 v[124:127], v220 offset:2048
	ds_read_b128 v[140:143], v247 offset:2048
	ds_read_b128 v[144:147], v221
	ds_read_b128 v[148:151], v248
	ds_read_b128 v[152:155], v221 offset:2048
	ds_read_b128 v[156:159], v248 offset:2048
	s_add_u32 s51, s52, 0xfff80080
	s_addc_u32 s54, s53, -1
	s_cmp_eq_u32 s41, 28
	s_cselect_b32 s57, s17, s54
	s_cselect_b32 s56, s27, s51
	s_cselect_b32 s55, s25, s39
	s_cselect_b32 s54, s35, s38
	v_lshl_add_u64 v[208:209], s[52:53], 0, v[194:195]
	s_add_i32 m0, s2, 0xc000
	ds_read_b128 v[160:163], v222
	ds_read_b128 v[164:167], v246
	ds_read_b128 v[168:171], v222 offset:2048
	ds_read_b128 v[172:175], v246 offset:2048
	ds_read_b128 v[176:179], v222 offset:4096
	ds_read_b128 v[180:183], v246 offset:4096
	ds_read_b128 v[200:203], v222 offset:6144
	ds_read_b128 v[204:207], v246 offset:6144
	global_load_lds_dwordx4 v[208:209], off
	v_lshl_add_u64 v[208:209], s[52:53], 0, v[192:193]
	s_add_i32 m0, s2, 0xe000
	s_nop 0
	global_load_lds_dwordx4 v[208:209], off
	s_waitcnt vmcnt(8)
	s_waitcnt lgkmcnt(0)
	s_barrier
	s_setprio 1
	s_waitcnt lgkmcnt(0)
	v_mfma_f32_16x16x32_bf16 v[136:139], v[104:107], v[160:163], v[136:139]
	v_mfma_f32_16x16x32_bf16 v[132:135], v[124:127], v[160:163], v[132:135]
	v_mfma_f32_16x16x32_bf16 v[116:119], v[104:107], v[168:171], v[116:119]
	v_mfma_f32_16x16x32_bf16 v[108:111], v[124:127], v[168:171], v[108:111]
	v_mfma_f32_16x16x32_bf16 v[92:95], v[104:107], v[176:179], v[92:95]
	v_mfma_f32_16x16x32_bf16 v[88:91], v[124:127], v[176:179], v[88:91]
	v_mfma_f32_16x16x32_bf16 v[76:79], v[104:107], v[200:203], v[76:79]
	v_mfma_f32_16x16x32_bf16 v[72:75], v[124:127], v[200:203], v[72:75]
	v_mfma_f32_16x16x32_bf16 v[136:139], v[112:115], v[164:167], v[136:139]
	v_mfma_f32_16x16x32_bf16 v[132:135], v[140:143], v[164:167], v[132:135]
	v_mfma_f32_16x16x32_bf16 v[116:119], v[112:115], v[172:175], v[116:119]
	v_mfma_f32_16x16x32_bf16 v[108:111], v[140:143], v[172:175], v[108:111]
	v_mfma_f32_16x16x32_bf16 v[92:95], v[112:115], v[180:183], v[92:95]
	v_mfma_f32_16x16x32_bf16 v[88:91], v[140:143], v[180:183], v[88:91]
	v_mfma_f32_16x16x32_bf16 v[76:79], v[112:115], v[204:207], v[76:79]
	v_mfma_f32_16x16x32_bf16 v[72:75], v[140:143], v[204:207], v[72:75]
	s_setprio 0
	s_setprio 1
	v_mfma_f32_16x16x32_bf16 v[128:131], v[144:147], v[160:163], v[128:131]
	v_mfma_f32_16x16x32_bf16 v[120:123], v[152:155], v[160:163], v[120:123]
	v_mfma_f32_16x16x32_bf16 v[100:103], v[144:147], v[168:171], v[100:103]
	v_mfma_f32_16x16x32_bf16 v[96:99], v[152:155], v[168:171], v[96:99]
	v_mfma_f32_16x16x32_bf16 v[84:87], v[144:147], v[176:179], v[84:87]
	v_mfma_f32_16x16x32_bf16 v[80:83], v[152:155], v[176:179], v[80:83]
	v_mfma_f32_16x16x32_bf16 v[68:71], v[144:147], v[200:203], v[68:71]
	v_mfma_f32_16x16x32_bf16 v[64:67], v[152:155], v[200:203], v[64:67]
	v_mfma_f32_16x16x32_bf16 v[128:131], v[148:151], v[164:167], v[128:131]
	v_mfma_f32_16x16x32_bf16 v[120:123], v[156:159], v[164:167], v[120:123]
	v_mfma_f32_16x16x32_bf16 v[100:103], v[148:151], v[172:175], v[100:103]
	v_mfma_f32_16x16x32_bf16 v[96:99], v[156:159], v[172:175], v[96:99]
	v_mfma_f32_16x16x32_bf16 v[84:87], v[148:151], v[180:183], v[84:87]
	v_mfma_f32_16x16x32_bf16 v[80:83], v[156:159], v[180:183], v[80:83]
	v_mfma_f32_16x16x32_bf16 v[68:71], v[148:151], v[204:207], v[68:71]
	v_mfma_f32_16x16x32_bf16 v[64:67], v[156:159], v[204:207], v[64:67]
	s_setprio 0
	s_barrier
	s_add_i32 s51, s0, s1
	v_lshl_add_u64 v[208:209], s[54:55], 0, v[186:187]
	s_mov_b32 m0, s51
	ds_read_b128 v[160:163], v222 offset:16384
	ds_read_b128 v[164:167], v246 offset:16384
	ds_read_b128 v[168:171], v222 offset:18432
	ds_read_b128 v[172:175], v246 offset:18432
	ds_read_b128 v[176:179], v222 offset:20480
	ds_read_b128 v[180:183], v246 offset:20480
	ds_read_b128 v[200:203], v222 offset:22528
	ds_read_b128 v[204:207], v246 offset:22528
	global_load_lds_dwordx4 v[208:209], off
	s_add_i32 m0, s51, 0x2000
	s_add_u32 s58, s54, 0x80000
	v_lshl_add_u64 v[210:211], s[54:55], 0, v[190:191]
	s_addc_u32 s59, s55, 0
	s_add_i32 s51, s34, s1
	global_load_lds_dwordx4 v[210:211], off
	v_lshl_add_u64 v[212:213], s[58:59], 0, v[186:187]
	s_mov_b32 m0, s51
	v_lshl_add_u64 v[214:215], s[56:57], 0, v[188:189]
	global_load_lds_dwordx4 v[212:213], off
	v_lshl_add_u64 v[212:213], s[58:59], 0, v[190:191]
	s_add_i32 m0, s51, 0x2000
	s_nop 0
	global_load_lds_dwordx4 v[212:213], off
	v_lshl_add_u64 v[212:213], s[56:57], 0, v[184:185]
	s_mov_b32 m0, s2
	s_nop 0
	global_load_lds_dwordx4 v[212:213], off
	s_mov_b32 m0, s4
	s_nop 0
	global_load_lds_dwordx4 v[214:215], off
	s_waitcnt vmcnt(8)
	s_waitcnt lgkmcnt(0)
	s_barrier
; #define PG8_STAGE(bufoff, gbase, voff) do { _Pragma("unroll") for (int _i = 0; _i < 2; ++_i) \
;         __builtin_amdgcn_global_load_lds((const unsigned*)((const char*)(gbase) + (voff)[_i]), (LAS unsigned*)(lds + (bufoff) + ldsw + _i * 8192), 16, 0, 0); } while (0)
; #define PG8_LDA(dst, b, h) do { _Pragma("unroll") for (int m = 0; m < 4; ++m) _Pragma("unroll") for (int k = 0; k < 2; ++k) dst[m][k] = *(const LAS bf16x8*)(lds + PG8_SA(b, h) + aoff + m * 2048 + k * 1024); } while (0)
; #define PG8_LDB(dst, b, h) do { _Pragma("unroll") for (int n = 0; n < 2; ++n) _Pragma("unroll") for (int k = 0; k < 2; ++k) dst[n][k] = *(const LAS bf16x8*)(lds + PG8_SB(b, h) + boff + n * 2048 + k * 1024); } while (0)
; #define PG8_MMA(ai, bj, At, Bt) do { __builtin_amdgcn_s_setprio(1); _Pragma("unroll") for (int m = 0; m < 4; ++m) _Pragma("unroll") for (int n = 0; n < 2; ++n) _Pragma("unroll") for (int k = 0; k < 2; ++k) \
;         acc[ai][bj][m][n] = __builtin_amdgcn_mfma_f32_16x16x32_bf16(Bt[n][k], At[m][k], acc[ai][bj][m][n], 0, 0, 0); __builtin_amdgcn_s_setprio(0); } while (0)
; #define PG8_WAIT_V(n) asm volatile("s_waitcnt vmcnt(" #n ")" ::: "memory")
; #define PG8_WAIT_L(n) asm volatile("s_waitcnt lgkmcnt(" #n ")" ::: "memory")
; #define PG8_BAR __builtin_amdgcn_s_barrier()
; #define PG8_SCHED __builtin_amdgcn_sched_barrier(0)
; template <class Epi, class Sched>
; __device__ __forceinline__ void gemm_phase(LAS unsigned char* lds, const int K, const int lda, const int ldb, const Sched& S, const Epi& E) {
;     ...
;             PG8_WAIT_V(8); PG8_WAIT_L(0); PG8_BAR; PG8_MMA(1, 0, At, B0); PG8_MMA(1, 1, At, B1); PG8_BAR; PG8_SCHED;
;             PG8_LDB(B0, 1, 0); PG8_LDB(B1, 1, 1); PG8_SCHED; PG8_LDA(At, 1, 0); PG8_STAGE(PG8_SA(0, 1), a2 + hA, voffA);
;             PG8_WAIT_V(8); PG8_WAIT_L(0); PG8_BAR; PG8_MMA(0, 0, At, B0); PG8_MMA(0, 1, At, B1); PG8_BAR; PG8_SCHED;
	s_setprio 1
	s_waitcnt lgkmcnt(0)
	v_mfma_f32_16x16x32_bf16 v[60:63], v[104:107], v[160:163], v[60:63]
	v_mfma_f32_16x16x32_bf16 v[56:59], v[124:127], v[160:163], v[56:59]
	v_mfma_f32_16x16x32_bf16 v[44:47], v[104:107], v[168:171], v[44:47]
	v_mfma_f32_16x16x32_bf16 v[40:43], v[124:127], v[168:171], v[40:43]
	v_mfma_f32_16x16x32_bf16 v[28:31], v[104:107], v[176:179], v[28:31]
	v_mfma_f32_16x16x32_bf16 v[24:27], v[124:127], v[176:179], v[24:27]
	v_mfma_f32_16x16x32_bf16 v[12:15], v[104:107], v[200:203], v[12:15]
	v_mfma_f32_16x16x32_bf16 v[8:11], v[124:127], v[200:203], v[8:11]
	v_mfma_f32_16x16x32_bf16 v[60:63], v[112:115], v[164:167], v[60:63]
	v_mfma_f32_16x16x32_bf16 v[56:59], v[140:143], v[164:167], v[56:59]
	v_mfma_f32_16x16x32_bf16 v[44:47], v[112:115], v[172:175], v[44:47]
	v_mfma_f32_16x16x32_bf16 v[40:43], v[140:143], v[172:175], v[40:43]
	v_mfma_f32_16x16x32_bf16 v[28:31], v[112:115], v[180:183], v[28:31]
	v_mfma_f32_16x16x32_bf16 v[24:27], v[140:143], v[180:183], v[24:27]
	v_mfma_f32_16x16x32_bf16 v[12:15], v[112:115], v[204:207], v[12:15]
	v_mfma_f32_16x16x32_bf16 v[8:11], v[140:143], v[204:207], v[8:11]
	s_setprio 0
	s_setprio 1
	v_mfma_f32_16x16x32_bf16 v[52:55], v[144:147], v[160:163], v[52:55]
	v_mfma_f32_16x16x32_bf16 v[48:51], v[152:155], v[160:163], v[48:51]
	v_mfma_f32_16x16x32_bf16 v[36:39], v[144:147], v[168:171], v[36:39]
	v_mfma_f32_16x16x32_bf16 v[32:35], v[152:155], v[168:171], v[32:35]
	v_mfma_f32_16x16x32_bf16 v[20:23], v[144:147], v[176:179], v[20:23]
	v_mfma_f32_16x16x32_bf16 v[16:19], v[152:155], v[176:179], v[16:19]
	v_mfma_f32_16x16x32_bf16 v[4:7], v[144:147], v[200:203], v[4:7]
	v_mfma_f32_16x16x32_bf16 v[0:3], v[152:155], v[200:203], v[0:3]
	v_mfma_f32_16x16x32_bf16 v[52:55], v[148:151], v[164:167], v[52:55]
	v_mfma_f32_16x16x32_bf16 v[48:51], v[156:159], v[164:167], v[48:51]
	v_mfma_f32_16x16x32_bf16 v[36:39], v[148:151], v[172:175], v[36:39]
	v_mfma_f32_16x16x32_bf16 v[32:35], v[156:159], v[172:175], v[32:35]
	v_mfma_f32_16x16x32_bf16 v[20:23], v[148:151], v[180:183], v[20:23]
	v_mfma_f32_16x16x32_bf16 v[16:19], v[156:159], v[180:183], v[16:19]
	v_mfma_f32_16x16x32_bf16 v[4:7], v[148:151], v[204:207], v[4:7]
	v_mfma_f32_16x16x32_bf16 v[0:3], v[156:159], v[204:207], v[0:3]
	s_setprio 0
	s_barrier
	s_add_i32 s51, 0, 0x18000
	s_add_i32 s58, 0, 0x1c000
	v_add_u32_e32 v140, s51, v217
	v_add_u32_e32 v250, s51, v249
	v_add_u32_e32 v156, s58, v217
	v_add_u32_e32 v251, s58, v249
	ds_read_b128 v[104:107], v140
	ds_read_b128 v[112:115], v250
	ds_read_b128 v[124:127], v140 offset:2048
	ds_read_b128 v[140:143], v250 offset:2048
	ds_read_b128 v[144:147], v156
	ds_read_b128 v[148:151], v251
	ds_read_b128 v[152:155], v156 offset:2048
	ds_read_b128 v[156:159], v251 offset:2048
	s_add_u32 s56, s56, 0x80000
	s_addc_u32 s57, s57, 0
	s_mov_b32 m0, s5
	v_lshl_add_u64 v[226:227], s[56:57], 0, v[184:185]
	ds_read_b128 v[160:163], v222 offset:32768
	ds_read_b128 v[164:167], v246 offset:32768
	ds_read_b128 v[168:171], v222 offset:34816
	ds_read_b128 v[172:175], v246 offset:34816
	ds_read_b128 v[176:179], v222 offset:36864
	ds_read_b128 v[180:183], v246 offset:36864
	ds_read_b128 v[200:203], v222 offset:38912
	ds_read_b128 v[204:207], v246 offset:38912
	global_load_lds_dwordx4 v[226:227], off
	v_lshl_add_u64 v[226:227], s[56:57], 0, v[188:189]
	s_mov_b32 m0, s6
	s_nop 0
	global_load_lds_dwordx4 v[226:227], off
	s_waitcnt vmcnt(8)
	s_waitcnt lgkmcnt(0)
	s_barrier
	s_setprio 1
	s_waitcnt lgkmcnt(0)
	v_mfma_f32_16x16x32_bf16 v[136:139], v[104:107], v[160:163], v[136:139]
	v_mfma_f32_16x16x32_bf16 v[132:135], v[124:127], v[160:163], v[132:135]
	v_mfma_f32_16x16x32_bf16 v[116:119], v[104:107], v[168:171], v[116:119]
	v_mfma_f32_16x16x32_bf16 v[108:111], v[124:127], v[168:171], v[108:111]
	v_mfma_f32_16x16x32_bf16 v[92:95], v[104:107], v[176:179], v[92:95]
	v_mfma_f32_16x16x32_bf16 v[88:91], v[124:127], v[176:179], v[88:91]
	v_mfma_f32_16x16x32_bf16 v[76:79], v[104:107], v[200:203], v[76:79]
	v_mfma_f32_16x16x32_bf16 v[72:75], v[124:127], v[200:203], v[72:75]
	v_mfma_f32_16x16x32_bf16 v[136:139], v[112:115], v[164:167], v[136:139]
	v_mfma_f32_16x16x32_bf16 v[132:135], v[140:143], v[164:167], v[132:135]
	v_mfma_f32_16x16x32_bf16 v[116:119], v[112:115], v[172:175], v[116:119]
	v_mfma_f32_16x16x32_bf16 v[108:111], v[140:143], v[172:175], v[108:111]
	v_mfma_f32_16x16x32_bf16 v[92:95], v[112:115], v[180:183], v[92:95]
	v_mfma_f32_16x16x32_bf16 v[88:91], v[140:143], v[180:183], v[88:91]
	v_mfma_f32_16x16x32_bf16 v[76:79], v[112:115], v[204:207], v[76:79]
	v_mfma_f32_16x16x32_bf16 v[72:75], v[140:143], v[204:207], v[72:75]
	s_setprio 0
	s_setprio 1
	v_mfma_f32_16x16x32_bf16 v[128:131], v[144:147], v[160:163], v[128:131]
	v_mfma_f32_16x16x32_bf16 v[120:123], v[152:155], v[160:163], v[120:123]
	v_mfma_f32_16x16x32_bf16 v[100:103], v[144:147], v[168:171], v[100:103]
	v_mfma_f32_16x16x32_bf16 v[96:99], v[152:155], v[168:171], v[96:99]
	v_mfma_f32_16x16x32_bf16 v[84:87], v[144:147], v[176:179], v[84:87]
	v_mfma_f32_16x16x32_bf16 v[80:83], v[152:155], v[176:179], v[80:83]
	v_mfma_f32_16x16x32_bf16 v[68:71], v[144:147], v[200:203], v[68:71]
	v_mfma_f32_16x16x32_bf16 v[64:67], v[152:155], v[200:203], v[64:67]
	v_mfma_f32_16x16x32_bf16 v[128:131], v[148:151], v[164:167], v[128:131]
	v_mfma_f32_16x16x32_bf16 v[120:123], v[156:159], v[164:167], v[120:123]
	v_mfma_f32_16x16x32_bf16 v[100:103], v[148:151], v[172:175], v[100:103]
	v_mfma_f32_16x16x32_bf16 v[96:99], v[156:159], v[172:175], v[96:99]
	v_mfma_f32_16x16x32_bf16 v[84:87], v[148:151], v[180:183], v[84:87]
	v_mfma_f32_16x16x32_bf16 v[80:83], v[156:159], v[180:183], v[80:83]
	v_mfma_f32_16x16x32_bf16 v[68:71], v[148:151], v[204:207], v[68:71]
	v_mfma_f32_16x16x32_bf16 v[64:67], v[156:159], v[204:207], v[64:67]
	s_setprio 0
	s_barrier
; #define PG8_STAGE(bufoff, gbase, voff) do { _Pragma("unroll") for (int _i = 0; _i < 2; ++_i) \
;         __builtin_amdgcn_global_load_lds((const unsigned*)((const char*)(gbase) + (voff)[_i]), (LAS unsigned*)(lds + (bufoff) + ldsw + _i * 8192), 16, 0, 0); } while (0)
; #define PG8_LDA(dst, b, h) do { _Pragma("unroll") for (int m = 0; m < 4; ++m) _Pragma("unroll") for (int k = 0; k < 2; ++k) dst[m][k] = *(const LAS bf16x8*)(lds + PG8_SA(b, h) + aoff + m * 2048 + k * 1024); } while (0)
; #define PG8_MMA(ai, bj, At, Bt) do { __builtin_amdgcn_s_setprio(1); _Pragma("unroll") for (int m = 0; m < 4; ++m) _Pragma("unroll") for (int n = 0; n < 2; ++n) _Pragma("unroll") for (int k = 0; k < 2; ++k) \
;         acc[ai][bj][m][n] = __builtin_amdgcn_mfma_f32_16x16x32_bf16(Bt[n][k], At[m][k], acc[ai][bj][m][n], 0, 0, 0); __builtin_amdgcn_s_setprio(0); } while (0)
; #define PG8_WAIT_V(n) asm volatile("s_waitcnt vmcnt(" #n ")" ::: "memory")
; #define PG8_WAIT_L(n) asm volatile("s_waitcnt lgkmcnt(" #n ")" ::: "memory")
; #define PG8_BAR __builtin_amdgcn_s_barrier()
; #define PG8_SCHED __builtin_amdgcn_sched_barrier(0)
; template <class Epi, class Sched>
; __device__ __forceinline__ void gemm_phase(LAS unsigned char* lds, const int K, const int lda, const int ldb, const Sched& S, const Epi& E) {
;     ...
;             PG8_LDA(At, 1, 1); PG8_STAGE(PG8_SB(1, 0), b3, voffB); PG8_STAGE(PG8_SB(1, 1), b3 + hB, voffB); PG8_STAGE(PG8_SA(1, 0), a3, voffA);
;             PG8_WAIT_V(8); PG8_WAIT_L(0); PG8_BAR; PG8_MMA(1, 0, At, B0); PG8_MMA(1, 1, At, B1); PG8_BAR; PG8_SCHED;
;         }
;         if (wr == 0) PG8_BAR;
	s_add_i32 s51, s51, s1
	v_lshl_add_u64 v[208:209], v[208:209], 0, s[20:21]
	s_mov_b32 m0, s51
	ds_read_b128 v[160:163], v222 offset:49152
	ds_read_b128 v[164:167], v246 offset:49152
	ds_read_b128 v[168:171], v222 offset:51200
	ds_read_b128 v[172:175], v246 offset:51200
	ds_read_b128 v[176:179], v222 offset:53248
	ds_read_b128 v[180:183], v246 offset:53248
	ds_read_b128 v[200:203], v222 offset:55296
	ds_read_b128 v[204:207], v246 offset:55296
	global_load_lds_dwordx4 v[208:209], off
	s_add_i32 m0, s51, 0x2000
	s_add_u32 s54, s54, 0x80080
	v_lshl_add_u64 v[208:209], v[210:211], 0, s[20:21]
	s_addc_u32 s55, s55, 0
	s_add_i32 s51, s58, s1
	global_load_lds_dwordx4 v[208:209], off
	v_lshl_add_u64 v[208:209], s[54:55], 0, v[186:187]
	s_mov_b32 m0, s51
	s_nop 0
	global_load_lds_dwordx4 v[208:209], off
	v_lshl_add_u64 v[208:209], s[54:55], 0, v[190:191]
	s_add_i32 m0, s51, 0x2000
	s_nop 0
	global_load_lds_dwordx4 v[208:209], off
	v_lshl_add_u64 v[208:209], v[212:213], 0, s[20:21]
	s_mov_b32 m0, s14
	s_nop 0
	global_load_lds_dwordx4 v[208:209], off
	v_lshl_add_u64 v[208:209], v[214:215], 0, s[20:21]
	s_mov_b32 m0, s15
	s_nop 0
	global_load_lds_dwordx4 v[208:209], off
	s_waitcnt vmcnt(8)
	s_waitcnt lgkmcnt(0)
	s_barrier
	s_setprio 1
	s_waitcnt lgkmcnt(0)
	v_mfma_f32_16x16x32_bf16 v[60:63], v[104:107], v[160:163], v[60:63]
	v_mfma_f32_16x16x32_bf16 v[56:59], v[124:127], v[160:163], v[56:59]
	v_mfma_f32_16x16x32_bf16 v[44:47], v[104:107], v[168:171], v[44:47]
	v_mfma_f32_16x16x32_bf16 v[40:43], v[124:127], v[168:171], v[40:43]
	v_mfma_f32_16x16x32_bf16 v[28:31], v[104:107], v[176:179], v[28:31]
	v_mfma_f32_16x16x32_bf16 v[24:27], v[124:127], v[176:179], v[24:27]
	v_mfma_f32_16x16x32_bf16 v[12:15], v[104:107], v[200:203], v[12:15]
	v_mfma_f32_16x16x32_bf16 v[8:11], v[124:127], v[200:203], v[8:11]
	v_mfma_f32_16x16x32_bf16 v[60:63], v[112:115], v[164:167], v[60:63]
	v_mfma_f32_16x16x32_bf16 v[56:59], v[140:143], v[164:167], v[56:59]
	v_mfma_f32_16x16x32_bf16 v[44:47], v[112:115], v[172:175], v[44:47]
	v_mfma_f32_16x16x32_bf16 v[40:43], v[140:143], v[172:175], v[40:43]
	v_mfma_f32_16x16x32_bf16 v[28:31], v[112:115], v[180:183], v[28:31]
	v_mfma_f32_16x16x32_bf16 v[24:27], v[140:143], v[180:183], v[24:27]
	v_mfma_f32_16x16x32_bf16 v[12:15], v[112:115], v[204:207], v[12:15]
	v_mfma_f32_16x16x32_bf16 v[8:11], v[140:143], v[204:207], v[8:11]
	s_setprio 0
	s_setprio 1
	v_mfma_f32_16x16x32_bf16 v[52:55], v[144:147], v[160:163], v[52:55]
	v_mfma_f32_16x16x32_bf16 v[48:51], v[152:155], v[160:163], v[48:51]
	v_mfma_f32_16x16x32_bf16 v[36:39], v[144:147], v[168:171], v[36:39]
	v_mfma_f32_16x16x32_bf16 v[32:35], v[152:155], v[168:171], v[32:35]
	v_mfma_f32_16x16x32_bf16 v[20:23], v[144:147], v[176:179], v[20:23]
	v_mfma_f32_16x16x32_bf16 v[16:19], v[152:155], v[176:179], v[16:19]
	v_mfma_f32_16x16x32_bf16 v[4:7], v[144:147], v[200:203], v[4:7]
	v_mfma_f32_16x16x32_bf16 v[0:3], v[152:155], v[200:203], v[0:3]
	v_mfma_f32_16x16x32_bf16 v[52:55], v[148:151], v[164:167], v[52:55]
	v_mfma_f32_16x16x32_bf16 v[48:51], v[156:159], v[164:167], v[48:51]
	v_mfma_f32_16x16x32_bf16 v[36:39], v[148:151], v[172:175], v[36:39]
	v_mfma_f32_16x16x32_bf16 v[32:35], v[156:159], v[172:175], v[32:35]
	v_mfma_f32_16x16x32_bf16 v[20:23], v[148:151], v[180:183], v[20:23]
	v_mfma_f32_16x16x32_bf16 v[16:19], v[156:159], v[180:183], v[16:19]
	v_mfma_f32_16x16x32_bf16 v[4:7], v[148:151], v[204:207], v[4:7]
	v_mfma_f32_16x16x32_bf16 v[0:3], v[156:159], v[204:207], v[0:3]
	s_setprio 0
	s_barrier
	s_add_i32 s41, s41, 2
	s_add_u32 s38, s38, 0x100
	s_addc_u32 s39, s39, 0
	s_add_u32 s52, s52, 0x100
	s_addc_u32 s53, s53, 0
	s_cmp_gt_u32 s41, 29
	s_cbranch_scc0 .LBB0_1372
	s_and_b64 vcc, exec, s[22:23]
	s_cbranch_vccz .LBB0_1375
	s_barrier

; #define PG8_STAGE(bufoff, gbase, voff) do { _Pragma("unroll") for (int _i = 0; _i < 2; ++_i) \
;         __builtin_amdgcn_global_load_lds((const unsigned*)((const char*)(gbase) + (voff)[_i]), (LAS unsigned*)(lds + (bufoff) + ldsw + _i * 8192), 16, 0, 0); } while (0)
; #define PG8_WAIT_V(n) asm volatile("s_waitcnt vmcnt(" #n ")" ::: "memory")
; #define PG8_BAR __builtin_amdgcn_s_barrier()
; template <class Epi, class Sched>
; __device__ __forceinline__ void gemm_phase(LAS unsigned char* lds, const int K, const int lda, const int ldb, const Sched& S, const Epi& E) {
;     ...
;     const int wid = __builtin_amdgcn_readfirstlane(tid >> 6), lane = tid & 63, wr = wid >> 2, wc = wid & 3, fr = lane & 15, fq = lane >> 4;
;     const int nt = K / BK;
;     unsigned voffA[2], voffB[2];
; #pragma unroll
;     for (int i = 0; i < 2; ++i) { int R, C; stage_rc(tid * 16 + i * 8192, R, C); const int Rb = (R & ~31) + perm32(R & 31);
;         voffA[i] = (unsigned)(R * lda + C) * 2u; voffB[i] = (unsigned)(Rb * ldb + C) * 2u; }
;     const size_t kstep = (size_t)(BK * 2);
;     const size_t hA = (size_t)HALF * lda * 2, hB = (size_t)HALF * ldb * 2;
;     const unsigned ldsw = (unsigned)wid * 1024u;
;     const int aoff = lds_byte(wr * 64 + fr, fq * 8), boff = lds_byte(wc * 32 + fr, fq * 8);
;     ...
;     Unit cur, nxt; int ui = 0;
;     if (!S.next(0, cur)) return;
;     f32x4 acc[2][2][4][2];
; #pragma unroll
;     for (int a = 0; a < 2; ++a)
; #pragma unroll
;         for (int b = 0; b < 2; ++b)
; #pragma unroll
;             for (int m = 0; m < 4; ++m)
; #pragma unroll
;                 for (int n = 0; n < 2; ++n) acc[a][b][m][n] = (f32x4){0.f, 0.f, 0.f, 0.f};
;     bf16x8 At[4][2], B0[2][2], B1[2][2];
;     const char* cA = S.aptr(cur); const char* cB = S.bptr(cur);
;     PG8_STAGE(PG8_SB(0, 0), cB, voffB); PG8_STAGE(PG8_SB(0, 1), cB + hB, voffB); PG8_STAGE(PG8_SA(0, 0), cA, voffA); PG8_STAGE(PG8_SA(0, 1), cA + hA, voffA);
;     if (wr == 1) PG8_BAR;
;     PG8_WAIT_V(2); PG8_BAR;
;     PG8_STAGE(PG8_SB(1, 0), cB + kstep, voffB); PG8_STAGE(PG8_SA(1, 0), cA + kstep, voffA); PG8_STAGE(PG8_SB(1, 1), cB + hB + kstep, voffB);
;     PG8_WAIT_V(6); PG8_BAR;
.LBB0_1439:
	s_add_u32 s16, s18, 0x2e00000
	s_addc_u32 s17, s19, 0
	s_and_b64 vcc, exec, s[60:61]
	s_cbranch_vccnz .LBB0_1498
	v_ashrrev_i32_e32 v1, 31, v8
	v_lshrrev_b32_e32 v1, 26, v1
	v_add_u32_e32 v1, v8, v1
	v_ashrrev_i32_e32 v9, 6, v1
	v_bfe_i32 v1, v8, 27, 1
	v_lshlrev_b32_e32 v0, 4, v8
	v_lshrrev_b32_e32 v1, 22, v1
	v_add_u32_e32 v1, v0, v1
	v_and_b32_e32 v1, 0xfffffc00, v1
	v_sub_u32_e32 v1, v0, v1
	v_lshrrev_b32_e32 v2, 4, v1
	v_bitop3_b32 v1, v2, v1, 32 bitop3:0x6c
	v_ashrrev_i32_e32 v3, 31, v1
	v_lshrrev_b32_e32 v3, 26, v3
	v_add_u32_e32 v3, v1, v3
	v_lshlrev_b32_e32 v2, 3, v9
	v_ashrrev_i32_e32 v10, 6, v3
	v_and_b32_e32 v3, 0xc0, v3
	v_and_b32_e32 v2, -16, v2
	v_sub_u32_e32 v1, v1, v3
	v_mov_b32_e32 v3, 1
	v_add_u32_e32 v2, v10, v2
	v_ashrrev_i16_sdwa v1, v3, sext(v1) dst_sel:DWORD dst_unused:UNUSED_PAD src0_sel:DWORD src1_sel:BYTE_0
	v_lshlrev_b32_e32 v4, 5, v9
	v_bfe_i32 v11, v1, 0, 16
	v_lshlrev_b32_e32 v1, 1, v2
	v_lshrrev_b32_e32 v5, 2, v2
	v_and_b32_e32 v6, 3, v10
	s_mov_b32 s2, 0xfffe0
	v_and_b32_e32 v4, 32, v4
	v_and_b32_e32 v1, 24, v1
	v_and_b32_e32 v5, 4, v5
	v_and_or_b32 v6, v2, s2, v6
	v_or3_b32 v1, v6, v5, v1
	v_add_lshl_u32 v4, v4, v11, 1
	v_add_u32_e32 v0, 0x2000, v0
	v_and_b32_e32 v106, 63, v254
	v_lshrrev_b32_e32 v107, 6, v254
	v_lshrrev_b32_e32 v108, 3, v106
	v_lshl_add_u32 v109, v107, 3, v108
	v_and_b32_e32 v110, 1, v107
	v_bfe_u32 v111, v106, 4, 2
	v_lshl_add_u32 v111, v110, 2, v111
	v_and_b32_e32 v101, 7, v106
	v_xor_b32_e32 v111, v101, v111
	v_lshlrev_b32_e32 v111, 4, v111
	v_lshl_add_u32 v100, v109, 12, v111
	v_add_u32_e32 v101, 0x40000, v100
	v_lshrrev_b32_e32 v109, 5, v106
	v_lshlrev_b32_e32 v109, 3, v109
	v_lshl_add_u32 v109, v110, 4, v109
	v_bfe_u32 v110, v107, 1, 1
	v_lshl_add_u32 v109, v110, 2, v109
	v_and_b32_e32 v110, 3, v108
	v_add_u32_e32 v109, v109, v110
	v_lshrrev_b32_e32 v110, 2, v107
	v_lshl_add_u32 v109, v110, 5, v109
	v_lshl_add_u32 v102, v109, 12, v111
	v_add_u32_e32 v103, 0x40000, v102
	v_and_b32_e32 v106, 15, v254
	v_bfe_u32 v108, v254, 4, 2
	v_bfe_u32 v109, v254, 1, 3
	v_xor_b32_e32 v108, v108, v109
	v_lshlrev_b32_e32 v108, 4, v108
	v_lshl_add_u32 v108, v106, 7, v108
	v_lshrrev_b32_e32 v109, 8, v254
	v_lshl_add_u32 v104, v109, 13, v108
	v_and_b32_e32 v109, 3, v107
	v_lshl_add_u32 v105, v109, 12, v108
	v_mov_b32_e32 v130, v102
	v_ashrrev_i32_e32 v1, 31, v0
	v_lshrrev_b32_e32 v1, 22, v1
	v_add_u32_e32 v1, v0, v1
	v_ashrrev_i32_e32 v12, 10, v1
	v_mul_i32_i24_e32 v1, 0x400, v12
	v_sub_u32_e32 v0, v0, v1
	v_lshrrev_b32_e32 v1, 4, v0
	v_bitop3_b32 v0, v1, v0, 32 bitop3:0x6c
	v_mov_b32_e32 v128, v100
	v_ashrrev_i32_e32 v2, 31, v0
	v_lshrrev_b32_e32 v2, 26, v2
	v_add_u32_e32 v2, v0, v2
	v_lshlrev_b32_e32 v1, 3, v12
	v_ashrrev_i32_e32 v13, 6, v2
	v_and_b32_e32 v2, 0xc0, v2
	v_and_b32_e32 v1, -16, v1
	v_sub_u32_e32 v0, v0, v2
	s_ashr_i32 s1, s0, 6
	v_add_u32_e32 v1, v13, v1
	v_ashrrev_i16_sdwa v0, v3, sext(v0) dst_sel:DWORD dst_unused:UNUSED_PAD src0_sel:DWORD src1_sel:BYTE_0
	v_and_b32_e32 v3, 3, v13
	s_ashr_i32 s6, s0, 8
	v_and_or_b32 v3, v1, s2, v3
	s_lshl_b32 s2, s1, 10
	s_add_u32 s4, s18, 0xa00000
	s_addc_u32 s5, s19, 0
	s_ashr_i32 s11, s10, 31
	s_ashr_i32 s55, s54, 31
	s_lshl_b64 s[8:9], s[10:11], 20
	s_lshl_b64 s[14:15], s[54:55], 20
	s_add_u32 s52, s4, s14
	v_lshlrev_b32_e32 v4, 5, v12
	v_bfe_i32 v14, v0, 0, 16
	v_lshlrev_b32_e32 v0, 1, v1
	v_lshrrev_b32_e32 v2, 2, v1
	s_addc_u32 s53, s5, s15
	s_add_i32 s14, s2, 0
	v_and_b32_e32 v4, 32, v4
	v_and_b32_e32 v0, 24, v0
	v_and_b32_e32 v2, 4, v2
	s_add_i32 m0, s14, 0x10000
	v_or3_b32 v0, v3, v2, v0
	v_add_lshl_u32 v2, v4, v14, 1
	global_load_lds_dwordx4 v130, s[52:53]
	s_add_i32 m0, s14, 0x12000
	v_mov_b32_e32 v134, v103
	s_add_u32 s20, s52, 0x80000
	global_load_lds_dwordx4 v134, s[52:53]
	s_addc_u32 s21, s53, 0
	s_add_i32 m0, s14, 0x14000
	v_mov_b32_e32 v132, v101
	global_load_lds_dwordx4 v130, s[20:21]
	s_add_i32 m0, s14, 0x16000
	s_add_u32 s56, s16, s8
	s_addc_u32 s57, s17, s9
	s_add_i32 s15, s14, 0x2000
	global_load_lds_dwordx4 v134, s[20:21]
	s_mov_b32 m0, s14
	s_add_u32 s8, s56, 0x80000
	global_load_lds_dwordx4 v128, s[56:57]
	s_mov_b32 m0, s15
	s_addc_u32 s9, s57, 0
	s_add_i32 s30, s14, 0x4000
	global_load_lds_dwordx4 v132, s[56:57]
	s_mov_b32 m0, s30
	s_add_i32 s31, s14, 0x6000
	global_load_lds_dwordx4 v128, s[8:9]
	s_mov_b32 m0, s31
	v_mov_b32_e32 v137, 0
	global_load_lds_dwordx4 v132, s[8:9]
	v_mov_b32_e32 v131, v137
	v_mov_b32_e32 v135, v137
	v_mov_b32_e32 v129, v137
	v_mov_b32_e32 v133, v137
	s_cmp_eq_u32 s6, 1
	s_mov_b32 s21, 0
	v_lshl_add_u64 v[6:7], s[52:53], 0, v[130:131]
	v_lshl_add_u64 v[4:5], s[52:53], 0, v[134:135]
	v_lshl_add_u64 v[0:1], s[56:57], 0, v[128:129]
	s_cselect_b64 s[22:23], -1, 0
	s_cmp_lg_u32 s6, 1
	v_lshl_add_u64 v[2:3], s[56:57], 0, v[132:133]
	s_cbranch_scc1 .LBB0_1442
	s_barrier
; #define LAS __attribute__((address_space(3)))
; __device__ __forceinline__ unsigned cvt_pk_bf16(float lo, float hi) { unsigned r; asm("v_cvt_pk_bf16_f32 %0, %1, %2" : "=v"(r) : "v"(lo), "v"(hi)); return r; }
; #define LDS_WAIT() asm volatile("s_waitcnt lgkmcnt(0)" ::: "memory")
; #define PG8_STAGE(bufoff, gbase, voff) do { _Pragma("unroll") for (int _i = 0; _i < 2; ++_i) \
;         __builtin_amdgcn_global_load_lds((const unsigned*)((const char*)(gbase) + (voff)[_i]), (LAS unsigned*)(lds + (bufoff) + ldsw + _i * 8192), 16, 0, 0); } while (0)
; template <class Epi, class Sched>
; __device__ __forceinline__ void gemm_phase(LAS unsigned char* lds, const int K, const int lda, const int ldb, const Sched& S, const Epi& E) {
;     ...
;     const int aoff = lds_byte(wr * 64 + fr, fq * 8), boff = lds_byte(wc * 32 + fr, fq * 8);
;     ...
;     Unit cur, nxt; int ui = 0;
;     if (!S.next(0, cur)) return;
;     f32x4 acc[2][2][4][2];
; #pragma unroll
;     for (int a = 0; a < 2; ++a)
; #pragma unroll
;         for (int b = 0; b < 2; ++b)
; #pragma unroll
;             for (int m = 0; m < 4; ++m)
; #pragma unroll
;                 for (int n = 0; n < 2; ++n) acc[a][b][m][n] = (f32x4){0.f, 0.f, 0.f, 0.f};
;     bf16x8 At[4][2], B0[2][2], B1[2][2];
;     const char* cA = S.aptr(cur); const char* cB = S.bptr(cur);
;     PG8_STAGE(PG8_SB(0, 0), cB, voffB); PG8_STAGE(PG8_SB(0, 1), cB + hB, voffB); PG8_STAGE(PG8_SA(0, 0), cA, voffA); PG8_STAGE(PG8_SA(0, 1), cA + hA, voffA);
;     if (wr == 1) PG8_BAR;
;     PG8_WAIT_V(2); PG8_BAR;
;     PG8_STAGE(PG8_SB(1, 0), cB + kstep, voffB); PG8_STAGE(PG8_SA(1, 0), cA + kstep, voffA); PG8_STAGE(PG8_SB(1, 1), cB + hB + kstep, voffB);
;     PG8_WAIT_V(6); PG8_BAR;
;     for (;;) {
; __device__ __forceinline__ void tstore_sub(const f32x4 (&v)[4][2], bf16_t* dst  , LAS unsigned char* x, int fr, int fq, int lane) {
;     ...
;                 const int ch = 8 * fq + 4 * n + j, tok = 16 * m + fr;
;                 const unsigned b = cvt_pk_bf16(v[m][n][j], 0.f);
;                 *(LAS unsigned short*)(x + ch * 128 + ((((tok >> 3) ^ fq) << 4) | ((tok & 7) << 1))) = (unsigned short)b;
;             }
;     LDS_WAIT();
; #pragma unroll
;     for (int i = 0; i < 4; ++i) {
;         const int q = lane + 64 * i, ch = q >> 3, tc = q & 7;
;         const u32x4 o = *(const LAS u32x4*)(x + ch * 128 + ((tc ^ ((ch >> 3) & 3)) << 4));
.LBB0_1442:
	v_and_b32_e32 v139, 15, v8
	v_and_b32_e32 v17, 48, v8
	v_lshlrev_b32_e32 v18, 2, v8
	s_and_b32 s8, s1, 3
	s_lshl_b32 s34, s6, 6
	s_lshl_b32 s6, s6, 13
	v_lshl_or_b32 v17, v139, 6, v17
	v_and_b32_e32 v18, 32, v18
	v_bitop3_b32 v19, v17, s6, v18 bitop3:0xde
	s_lshl_b32 s9, s8, 5
	s_lshl_b32 s6, s8, 12
	s_add_u32 s24, s18, 0x200000
	s_mov_b64 s[26:27], 0x80
	s_addc_u32 s25, s19, 0
	s_add_i32 m0, s14, 0x18000
	v_lshl_add_u64 v[6:7], v[6:7], 0, s[26:27]
	s_waitcnt vmcnt(2)
	s_barrier
	global_load_lds_dwordx4 v[6:7], off
	v_lshl_add_u64 v[4:5], v[4:5], 0, s[26:27]
	s_add_i32 m0, s14, 0x1a000
	s_add_i32 s35, s14, 0x8000
	s_add_i32 s38, s14, 0xa000
	v_mov_b32_e32 v143, v105
	global_load_lds_dwordx4 v[4:5], off
	v_lshl_add_u64 v[0:1], v[0:1], 0, s[26:27]
	s_mov_b32 m0, s35
	s_add_u32 s6, s52, 0x80080
	global_load_lds_dwordx4 v[0:1], off
	v_lshl_add_u64 v[0:1], v[2:3], 0, s[26:27]
	s_mov_b32 m0, s38
	s_addc_u32 s7, s53, 0
	global_load_lds_dwordx4 v[0:1], off
	s_add_i32 m0, s14, 0x1c000
	v_lshl_add_u64 v[0:1], s[6:7], 0, v[130:131]
	global_load_lds_dwordx4 v[0:1], off
	v_lshl_add_u64 v[0:1], s[6:7], 0, v[134:135]
	s_add_i32 m0, s14, 0x1e000
	s_cmpk_lt_u32 s0, 0x100
	global_load_lds_dwordx4 v[0:1], off
	s_cselect_b64 s[28:29], -1, 0
	s_lshl_b32 s0, s1, 12
	v_bfe_u32 v15, v8, 4, 2
	s_add_i32 s0, s0, 0
	v_bfe_u32 v2, v8, 3, 1
	v_bfe_u32 v7, v8, 3, 3
	v_lshlrev_b32_e32 v16, 3, v15
	s_add_i32 s0, s0, 0x20000
	v_lshlrev_b32_e32 v1, 10, v15
	v_xor_b32_e32 v3, v2, v15
	v_bitop3_b32 v4, v2, v15, 2 bitop3:0x36
	v_bitop3_b32 v5, v2, v15, 4 bitop3:0x36
	v_bitop3_b32 v2, v2, v15, 6 bitop3:0x36
	v_or_b32_e32 v15, 8, v7
	v_and_b32_e32 v141, 63, v8
	v_lshlrev_b32_e32 v0, 1, v8
	v_and_b32_e32 v6, 7, v8
	v_lshl_add_u32 v8, v7, 7, s0
	v_lshlrev_b32_e32 v138, 15, v7
	v_lshl_add_u32 v17, v15, 7, s0
	v_lshlrev_b32_e32 v140, 15, v15
	v_or_b32_e32 v15, 16, v7
	v_or_b32_e32 v7, 24, v7
	v_lshl_add_u32 v20, v15, 7, s0
	v_lshlrev_b32_e32 v142, 15, v15
	v_lshl_add_u32 v15, v7, 7, s0
	v_lshlrev_b32_e32 v144, 15, v7
	v_lshlrev_b32_e32 v7, 15, v12
	s_add_u32 s39, s18, 0x16e00000
	v_and_b32_e32 v7, 0xffff0000, v7
	s_addc_u32 s43, s19, 0
	v_lshl_add_u32 v7, v13, 12, v7
	v_and_b32_e32 v12, 1, v12
	s_add_u32 s64, s18, 0x12e00000
	v_and_b32_e32 v0, 14, v0
	v_lshl_or_b32 v7, v12, 6, v7
	s_addc_u32 s65, s19, 0
	s_lshl_b32 s1, s8, 20
	v_add_u32_e32 v0, s0, v0
	s_lshl_b32 s0, s8, 2
	v_mov_b32_e32 v146, v101
	v_lshlrev_b32_e32 v7, 15, v9
	s_add_u32 s0, s18, s0
	v_and_b32_e32 v7, 0xffff0000, v7
	s_addc_u32 s8, s19, 0
	v_lshl_add_u32 v7, v10, 12, v7
	v_and_b32_e32 v9, 1, v9
	s_waitcnt vmcnt(6)
	v_lshl_add_u32 v3, v3, 4, v0
	v_lshl_add_u32 v4, v4, 4, v0
	v_lshl_add_u32 v5, v5, 4, v0
	v_lshl_add_u32 v2, v2, 4, v0
	v_lshlrev_b32_e32 v0, 3, v6
	v_lshlrev_b32_e32 v6, 4, v6
	s_add_u32 s66, s0, 0x600000
	v_lshl_or_b32 v7, v9, 6, v7
	v_xor_b32_e32 v18, 16, v6
	v_xor_b32_e32 v21, 32, v6
	v_xor_b32_e32 v22, 48, v6
	s_addc_u32 s67, s8, 0
	v_mov_b32_e32 v148, v100
	s_add_i32 s72, 0, 0x10000
	s_add_i32 s73, 0, 0x14000
	v_mbcnt_lo_u32_b32 v7, -1, 0
	v_cmp_gt_u32_e64 s[6:7], 16, v141
	s_or_b32 s68, s1, 0x400000
	s_ashr_i32 s69, s3, 31
	s_ashr_i32 s70, s33, 31
	v_mov_b32_e32 v147, v137
	v_mov_b32_e32 v149, v137
	s_movk_i32 s71, 0x1c1
	s_mov_b64 s[36:37], 0x100
	v_mov_b32_e32 v145, v104
	v_mbcnt_hi_u32_b32 v157, -1, v7
	s_mov_b32 s42, 0x3a000000
	s_mov_b32 s74, 0x800000
	v_lshlrev_b32_e32 v136, 1, v0
	s_lshl_b32 s20, s1, 1
	s_lshl_b32 s75, s9, 1
	v_lshlrev_b32_e32 v150, 1, v16
	v_mov_b64_e32 v[152:153], 0xe00
	v_mov_b64_e32 v[154:155], 0xdff
	v_add_u32_e32 v235, s72, v143
	v_add_u32_e32 v236, s73, v143
	v_xor_b32_e32 v248, 64, v145
	v_xor_b32_e32 v249, 64, v235
	v_xor_b32_e32 v250, 64, v236
	v_xor_b32_e32 v251, 64, v143
	v_mov_b32_e32 v156, 0x358637bd
	v_add_u32_e32 v237, v3, v1
	v_add_u32_e32 v238, v4, v1
	v_add_u32_e32 v239, v5, v1
	v_add_u32_e32 v240, v2, v1
	v_add_u32_e32 v241, v8, v6
	v_add_u32_e32 v242, v17, v18
	v_add_u32_e32 v243, v20, v21
	v_add_u32_e32 v244, v15, v22
	s_mov_b32 s76, s21
	s_barrier
	s_branch .LBB0_1445

; #define PG8_STAGE(bufoff, gbase, voff) do { _Pragma("unroll") for (int _i = 0; _i < 2; ++_i) \
;         __builtin_amdgcn_global_load_lds((const unsigned*)((const char*)(gbase) + (voff)[_i]), (LAS unsigned*)(lds + (bufoff) + ldsw + _i * 8192), 16, 0, 0); } while (0)
; #define PG8_LDA(dst, b, h) do { _Pragma("unroll") for (int m = 0; m < 4; ++m) _Pragma("unroll") for (int k = 0; k < 2; ++k) dst[m][k] = *(const LAS bf16x8*)(lds + PG8_SA(b, h) + aoff + m * 2048 + k * 1024); } while (0)
; #define PG8_LDB(dst, b, h) do { _Pragma("unroll") for (int n = 0; n < 2; ++n) _Pragma("unroll") for (int k = 0; k < 2; ++k) dst[n][k] = *(const LAS bf16x8*)(lds + PG8_SB(b, h) + boff + n * 2048 + k * 1024); } while (0)
; #define PG8_MMA(ai, bj, At, Bt) do { __builtin_amdgcn_s_setprio(1); _Pragma("unroll") for (int m = 0; m < 4; ++m) _Pragma("unroll") for (int n = 0; n < 2; ++n) _Pragma("unroll") for (int k = 0; k < 2; ++k) \
;         acc[ai][bj][m][n] = __builtin_amdgcn_mfma_f32_16x16x32_bf16(Bt[n][k], At[m][k], acc[ai][bj][m][n], 0, 0, 0); __builtin_amdgcn_s_setprio(0); } while (0)
; #define PG8_WAIT_V(n) asm volatile("s_waitcnt vmcnt(" #n ")" ::: "memory")
; #define PG8_WAIT_L(n) asm volatile("s_waitcnt lgkmcnt(" #n ")" ::: "memory")
; #define PG8_BAR __builtin_amdgcn_s_barrier()
; #define PG8_SCHED __builtin_amdgcn_sched_barrier(0)
; template <class Epi, class Sched>
; __device__ __forceinline__ void gemm_phase(LAS unsigned char* lds, const int K, const int lda, const int ldb, const Sched& S, const Epi& E) {
;     ...
;             PG8_LDB(B0, 0, 0); PG8_LDB(B1, 0, 1); PG8_SCHED; PG8_LDA(At, 0, 0); PG8_STAGE(PG8_SA(1, 1), a1 + hA, voffA);
;             PG8_WAIT_V(8); PG8_WAIT_L(0); PG8_BAR; PG8_MMA(0, 0, At, B0); PG8_MMA(0, 1, At, B1); PG8_BAR; PG8_SCHED;
;             PG8_LDA(At, 0, 1); PG8_STAGE(PG8_SB(0, 0), b2, voffB); PG8_STAGE(PG8_SB(0, 1), b2 + hB, voffB); PG8_STAGE(PG8_SA(0, 0), a2, voffA);
;             PG8_WAIT_V(8); PG8_WAIT_L(0); PG8_BAR; PG8_MMA(1, 0, At, B0); PG8_MMA(1, 1, At, B1); PG8_BAR; PG8_SCHED;
.LBB0_1448:
	s_waitcnt lgkmcnt(0)
	ds_read_b128 v[158:161], v235
	ds_read_b128 v[162:165], v249
	ds_read_b128 v[166:169], v235 offset:2048
	ds_read_b128 v[170:173], v249 offset:2048
	ds_read_b128 v[174:177], v236
	ds_read_b128 v[178:181], v250
	ds_read_b128 v[182:185], v236 offset:2048
	ds_read_b128 v[186:189], v250 offset:2048
	s_add_u32 s56, s52, 0xfff80080
	s_addc_u32 s57, s53, -1
	s_cmp_eq_u32 s55, 28
	s_cselect_b32 s59, s0, s57
	s_cselect_b32 s58, s1, s56
	s_cselect_b32 s57, s11, s47
	s_cselect_b32 s56, s41, s45
	v_lshl_add_u64 v[222:223], s[52:53], 0, v[148:149]
	s_add_i32 m0, s14, 0xc000
	ds_read_b128 v[190:193], v145
	ds_read_b128 v[194:197], v248
	ds_read_b128 v[198:201], v145 offset:2048
	ds_read_b128 v[202:205], v248 offset:2048
	ds_read_b128 v[206:209], v145 offset:4096
	ds_read_b128 v[210:213], v248 offset:4096
	ds_read_b128 v[214:217], v145 offset:6144
	ds_read_b128 v[218:221], v248 offset:6144
	global_load_lds_dwordx4 v[222:223], off
	v_lshl_add_u64 v[222:223], s[52:53], 0, v[146:147]
	s_add_i32 m0, s14, 0xe000
	s_nop 0
	global_load_lds_dwordx4 v[222:223], off
	s_waitcnt vmcnt(8)
	s_waitcnt lgkmcnt(0)
	s_barrier
	s_setprio 1
	s_waitcnt lgkmcnt(0)
	v_mfma_f32_16x16x32_bf16 v[124:127], v[158:161], v[190:193], v[124:127]
	v_mfma_f32_16x16x32_bf16 v[116:119], v[166:169], v[190:193], v[116:119]
	v_mfma_f32_16x16x32_bf16 v[108:111], v[158:161], v[198:201], v[108:111]
	v_mfma_f32_16x16x32_bf16 v[100:103], v[166:169], v[198:201], v[100:103]
	v_mfma_f32_16x16x32_bf16 v[92:95], v[158:161], v[206:209], v[92:95]
	v_mfma_f32_16x16x32_bf16 v[84:87], v[166:169], v[206:209], v[84:87]
	v_mfma_f32_16x16x32_bf16 v[76:79], v[158:161], v[214:217], v[76:79]
	v_mfma_f32_16x16x32_bf16 v[68:71], v[166:169], v[214:217], v[68:71]
	v_mfma_f32_16x16x32_bf16 v[124:127], v[162:165], v[194:197], v[124:127]
	v_mfma_f32_16x16x32_bf16 v[116:119], v[170:173], v[194:197], v[116:119]
	v_mfma_f32_16x16x32_bf16 v[108:111], v[162:165], v[202:205], v[108:111]
	v_mfma_f32_16x16x32_bf16 v[100:103], v[170:173], v[202:205], v[100:103]
	v_mfma_f32_16x16x32_bf16 v[92:95], v[162:165], v[210:213], v[92:95]
	v_mfma_f32_16x16x32_bf16 v[84:87], v[170:173], v[210:213], v[84:87]
	v_mfma_f32_16x16x32_bf16 v[76:79], v[162:165], v[218:221], v[76:79]
	v_mfma_f32_16x16x32_bf16 v[68:71], v[170:173], v[218:221], v[68:71]
	s_setprio 0
	s_setprio 1
	v_mfma_f32_16x16x32_bf16 v[120:123], v[174:177], v[190:193], v[120:123]
	v_mfma_f32_16x16x32_bf16 v[112:115], v[182:185], v[190:193], v[112:115]
	v_mfma_f32_16x16x32_bf16 v[104:107], v[174:177], v[198:201], v[104:107]
	v_mfma_f32_16x16x32_bf16 v[96:99], v[182:185], v[198:201], v[96:99]
	v_mfma_f32_16x16x32_bf16 v[88:91], v[174:177], v[206:209], v[88:91]
	v_mfma_f32_16x16x32_bf16 v[80:83], v[182:185], v[206:209], v[80:83]
	v_mfma_f32_16x16x32_bf16 v[72:75], v[174:177], v[214:217], v[72:75]
	v_mfma_f32_16x16x32_bf16 v[64:67], v[182:185], v[214:217], v[64:67]
	v_mfma_f32_16x16x32_bf16 v[120:123], v[178:181], v[194:197], v[120:123]
	v_mfma_f32_16x16x32_bf16 v[112:115], v[186:189], v[194:197], v[112:115]
	v_mfma_f32_16x16x32_bf16 v[104:107], v[178:181], v[202:205], v[104:107]
	v_mfma_f32_16x16x32_bf16 v[96:99], v[186:189], v[202:205], v[96:99]
	v_mfma_f32_16x16x32_bf16 v[88:91], v[178:181], v[210:213], v[88:91]
	v_mfma_f32_16x16x32_bf16 v[80:83], v[186:189], v[210:213], v[80:83]
	v_mfma_f32_16x16x32_bf16 v[72:75], v[178:181], v[218:221], v[72:75]
	v_mfma_f32_16x16x32_bf16 v[64:67], v[186:189], v[218:221], v[64:67]
	s_setprio 0
	s_barrier
	s_add_i32 s60, s72, s2
	v_lshl_add_u64 v[222:223], s[56:57], 0, v[130:131]
	s_mov_b32 m0, s60
	ds_read_b128 v[190:193], v145 offset:16384
	ds_read_b128 v[194:197], v248 offset:16384
	ds_read_b128 v[198:201], v145 offset:18432
	ds_read_b128 v[202:205], v248 offset:18432
	ds_read_b128 v[206:209], v145 offset:20480
	ds_read_b128 v[210:213], v248 offset:20480
	ds_read_b128 v[214:217], v145 offset:22528
	ds_read_b128 v[218:221], v248 offset:22528
	global_load_lds_dwordx4 v[222:223], off
	s_add_i32 m0, s60, 0x2000
	s_add_u32 s60, s56, 0x80000
	v_lshl_add_u64 v[224:225], s[56:57], 0, v[134:135]
	s_addc_u32 s61, s57, 0
	s_add_i32 s62, s73, s2
	global_load_lds_dwordx4 v[224:225], off
	v_lshl_add_u64 v[226:227], s[60:61], 0, v[130:131]
	s_mov_b32 m0, s62
	v_lshl_add_u64 v[228:229], s[58:59], 0, v[132:133]
	global_load_lds_dwordx4 v[226:227], off
	v_lshl_add_u64 v[226:227], s[60:61], 0, v[134:135]
	s_add_i32 m0, s62, 0x2000
	s_nop 0
	global_load_lds_dwordx4 v[226:227], off
	v_lshl_add_u64 v[226:227], s[58:59], 0, v[128:129]
	s_mov_b32 m0, s14
	s_nop 0
	global_load_lds_dwordx4 v[226:227], off
	s_mov_b32 m0, s15
	s_nop 0
	global_load_lds_dwordx4 v[228:229], off
	s_waitcnt vmcnt(8)
	s_waitcnt lgkmcnt(0)
	s_barrier
; #define PG8_STAGE(bufoff, gbase, voff) do { _Pragma("unroll") for (int _i = 0; _i < 2; ++_i) \
;         __builtin_amdgcn_global_load_lds((const unsigned*)((const char*)(gbase) + (voff)[_i]), (LAS unsigned*)(lds + (bufoff) + ldsw + _i * 8192), 16, 0, 0); } while (0)
; #define PG8_LDA(dst, b, h) do { _Pragma("unroll") for (int m = 0; m < 4; ++m) _Pragma("unroll") for (int k = 0; k < 2; ++k) dst[m][k] = *(const LAS bf16x8*)(lds + PG8_SA(b, h) + aoff + m * 2048 + k * 1024); } while (0)
; #define PG8_LDB(dst, b, h) do { _Pragma("unroll") for (int n = 0; n < 2; ++n) _Pragma("unroll") for (int k = 0; k < 2; ++k) dst[n][k] = *(const LAS bf16x8*)(lds + PG8_SB(b, h) + boff + n * 2048 + k * 1024); } while (0)
; #define PG8_MMA(ai, bj, At, Bt) do { __builtin_amdgcn_s_setprio(1); _Pragma("unroll") for (int m = 0; m < 4; ++m) _Pragma("unroll") for (int n = 0; n < 2; ++n) _Pragma("unroll") for (int k = 0; k < 2; ++k) \
;         acc[ai][bj][m][n] = __builtin_amdgcn_mfma_f32_16x16x32_bf16(Bt[n][k], At[m][k], acc[ai][bj][m][n], 0, 0, 0); __builtin_amdgcn_s_setprio(0); } while (0)
; #define PG8_WAIT_V(n) asm volatile("s_waitcnt vmcnt(" #n ")" ::: "memory")
; #define PG8_WAIT_L(n) asm volatile("s_waitcnt lgkmcnt(" #n ")" ::: "memory")
; #define PG8_BAR __builtin_amdgcn_s_barrier()
; #define PG8_SCHED __builtin_amdgcn_sched_barrier(0)
; template <class Epi, class Sched>
; __device__ __forceinline__ void gemm_phase(LAS unsigned char* lds, const int K, const int lda, const int ldb, const Sched& S, const Epi& E) {
;     ...
;             PG8_WAIT_V(8); PG8_WAIT_L(0); PG8_BAR; PG8_MMA(1, 0, At, B0); PG8_MMA(1, 1, At, B1); PG8_BAR; PG8_SCHED;
;             PG8_LDB(B0, 1, 0); PG8_LDB(B1, 1, 1); PG8_SCHED; PG8_LDA(At, 1, 0); PG8_STAGE(PG8_SA(0, 1), a2 + hA, voffA);
;             PG8_WAIT_V(8); PG8_WAIT_L(0); PG8_BAR; PG8_MMA(0, 0, At, B0); PG8_MMA(0, 1, At, B1); PG8_BAR; PG8_SCHED;
	s_setprio 1
	s_waitcnt lgkmcnt(0)
	v_mfma_f32_16x16x32_bf16 v[60:63], v[158:161], v[190:193], v[60:63]
	v_mfma_f32_16x16x32_bf16 v[52:55], v[166:169], v[190:193], v[52:55]
	v_mfma_f32_16x16x32_bf16 v[44:47], v[158:161], v[198:201], v[44:47]
	v_mfma_f32_16x16x32_bf16 v[36:39], v[166:169], v[198:201], v[36:39]
	v_mfma_f32_16x16x32_bf16 v[28:31], v[158:161], v[206:209], v[28:31]
	v_mfma_f32_16x16x32_bf16 v[20:23], v[166:169], v[206:209], v[20:23]
	v_mfma_f32_16x16x32_bf16 v[12:15], v[158:161], v[214:217], v[12:15]
	v_mfma_f32_16x16x32_bf16 v[4:7], v[166:169], v[214:217], v[4:7]
	v_mfma_f32_16x16x32_bf16 v[60:63], v[162:165], v[194:197], v[60:63]
	v_mfma_f32_16x16x32_bf16 v[52:55], v[170:173], v[194:197], v[52:55]
	v_mfma_f32_16x16x32_bf16 v[44:47], v[162:165], v[202:205], v[44:47]
	v_mfma_f32_16x16x32_bf16 v[36:39], v[170:173], v[202:205], v[36:39]
	v_mfma_f32_16x16x32_bf16 v[28:31], v[162:165], v[210:213], v[28:31]
	v_mfma_f32_16x16x32_bf16 v[20:23], v[170:173], v[210:213], v[20:23]
	v_mfma_f32_16x16x32_bf16 v[12:15], v[162:165], v[218:221], v[12:15]
	v_mfma_f32_16x16x32_bf16 v[4:7], v[170:173], v[218:221], v[4:7]
	s_setprio 0
	s_setprio 1
	v_mfma_f32_16x16x32_bf16 v[56:59], v[174:177], v[190:193], v[56:59]
	v_mfma_f32_16x16x32_bf16 v[48:51], v[182:185], v[190:193], v[48:51]
	v_mfma_f32_16x16x32_bf16 v[40:43], v[174:177], v[198:201], v[40:43]
	v_mfma_f32_16x16x32_bf16 v[32:35], v[182:185], v[198:201], v[32:35]
	v_mfma_f32_16x16x32_bf16 v[24:27], v[174:177], v[206:209], v[24:27]
	v_mfma_f32_16x16x32_bf16 v[16:19], v[182:185], v[206:209], v[16:19]
	v_mfma_f32_16x16x32_bf16 v[8:11], v[174:177], v[214:217], v[8:11]
	v_mfma_f32_16x16x32_bf16 v[0:3], v[182:185], v[214:217], v[0:3]
	v_mfma_f32_16x16x32_bf16 v[56:59], v[178:181], v[194:197], v[56:59]
	v_mfma_f32_16x16x32_bf16 v[48:51], v[186:189], v[194:197], v[48:51]
	v_mfma_f32_16x16x32_bf16 v[40:43], v[178:181], v[202:205], v[40:43]
	v_mfma_f32_16x16x32_bf16 v[32:35], v[186:189], v[202:205], v[32:35]
	v_mfma_f32_16x16x32_bf16 v[24:27], v[178:181], v[210:213], v[24:27]
	v_mfma_f32_16x16x32_bf16 v[16:19], v[186:189], v[210:213], v[16:19]
	v_mfma_f32_16x16x32_bf16 v[8:11], v[178:181], v[218:221], v[8:11]
	v_mfma_f32_16x16x32_bf16 v[0:3], v[186:189], v[218:221], v[0:3]
	s_setprio 0
	s_barrier
	s_add_i32 s60, 0, 0x18000
	v_add_u32_e32 v151, s60, v143
	v_add_u32_e32 v252, s60, v251
	s_add_i32 s61, 0, 0x1c000
	ds_read_b128 v[158:161], v151
	ds_read_b128 v[162:165], v252
	ds_read_b128 v[166:169], v151 offset:2048
	ds_read_b128 v[170:173], v252 offset:2048
	v_add_u32_e32 v151, s61, v143
	v_add_u32_e32 v252, s61, v251
	ds_read_b128 v[174:177], v151
	ds_read_b128 v[178:181], v252
	ds_read_b128 v[182:185], v151 offset:2048
	ds_read_b128 v[186:189], v252 offset:2048
	s_add_u32 s58, s58, 0x80000
	s_addc_u32 s59, s59, 0
	s_mov_b32 m0, s30
	v_lshl_add_u64 v[230:231], s[58:59], 0, v[128:129]
	ds_read_b128 v[190:193], v145 offset:32768
	ds_read_b128 v[194:197], v248 offset:32768
	ds_read_b128 v[198:201], v145 offset:34816
	ds_read_b128 v[202:205], v248 offset:34816
	ds_read_b128 v[206:209], v145 offset:36864
	ds_read_b128 v[210:213], v248 offset:36864
	ds_read_b128 v[214:217], v145 offset:38912
	ds_read_b128 v[218:221], v248 offset:38912
	global_load_lds_dwordx4 v[230:231], off
	v_lshl_add_u64 v[230:231], s[58:59], 0, v[132:133]
	s_mov_b32 m0, s31
	s_nop 0
	global_load_lds_dwordx4 v[230:231], off
	s_waitcnt vmcnt(8)
	s_waitcnt lgkmcnt(0)
	s_barrier
	s_setprio 1
	s_waitcnt lgkmcnt(0)
	v_mfma_f32_16x16x32_bf16 v[124:127], v[158:161], v[190:193], v[124:127]
	v_mfma_f32_16x16x32_bf16 v[116:119], v[166:169], v[190:193], v[116:119]
	v_mfma_f32_16x16x32_bf16 v[108:111], v[158:161], v[198:201], v[108:111]
	v_mfma_f32_16x16x32_bf16 v[100:103], v[166:169], v[198:201], v[100:103]
	v_mfma_f32_16x16x32_bf16 v[92:95], v[158:161], v[206:209], v[92:95]
	v_mfma_f32_16x16x32_bf16 v[84:87], v[166:169], v[206:209], v[84:87]
	v_mfma_f32_16x16x32_bf16 v[76:79], v[158:161], v[214:217], v[76:79]
	v_mfma_f32_16x16x32_bf16 v[68:71], v[166:169], v[214:217], v[68:71]
	v_mfma_f32_16x16x32_bf16 v[124:127], v[162:165], v[194:197], v[124:127]
	v_mfma_f32_16x16x32_bf16 v[116:119], v[170:173], v[194:197], v[116:119]
	v_mfma_f32_16x16x32_bf16 v[108:111], v[162:165], v[202:205], v[108:111]
	v_mfma_f32_16x16x32_bf16 v[100:103], v[170:173], v[202:205], v[100:103]
	v_mfma_f32_16x16x32_bf16 v[92:95], v[162:165], v[210:213], v[92:95]
	v_mfma_f32_16x16x32_bf16 v[84:87], v[170:173], v[210:213], v[84:87]
	v_mfma_f32_16x16x32_bf16 v[76:79], v[162:165], v[218:221], v[76:79]
	v_mfma_f32_16x16x32_bf16 v[68:71], v[170:173], v[218:221], v[68:71]
	s_setprio 0
	s_setprio 1
	v_mfma_f32_16x16x32_bf16 v[120:123], v[174:177], v[190:193], v[120:123]
	v_mfma_f32_16x16x32_bf16 v[112:115], v[182:185], v[190:193], v[112:115]
	v_mfma_f32_16x16x32_bf16 v[104:107], v[174:177], v[198:201], v[104:107]
	v_mfma_f32_16x16x32_bf16 v[96:99], v[182:185], v[198:201], v[96:99]
	v_mfma_f32_16x16x32_bf16 v[88:91], v[174:177], v[206:209], v[88:91]
	v_mfma_f32_16x16x32_bf16 v[80:83], v[182:185], v[206:209], v[80:83]
	v_mfma_f32_16x16x32_bf16 v[72:75], v[174:177], v[214:217], v[72:75]
	v_mfma_f32_16x16x32_bf16 v[64:67], v[182:185], v[214:217], v[64:67]
	v_mfma_f32_16x16x32_bf16 v[120:123], v[178:181], v[194:197], v[120:123]
	v_mfma_f32_16x16x32_bf16 v[112:115], v[186:189], v[194:197], v[112:115]
	v_mfma_f32_16x16x32_bf16 v[104:107], v[178:181], v[202:205], v[104:107]
	v_mfma_f32_16x16x32_bf16 v[96:99], v[186:189], v[202:205], v[96:99]
	v_mfma_f32_16x16x32_bf16 v[88:91], v[178:181], v[210:213], v[88:91]
	v_mfma_f32_16x16x32_bf16 v[80:83], v[186:189], v[210:213], v[80:83]
	v_mfma_f32_16x16x32_bf16 v[72:75], v[178:181], v[218:221], v[72:75]
	v_mfma_f32_16x16x32_bf16 v[64:67], v[186:189], v[218:221], v[64:67]
	s_setprio 0
	s_barrier
; #define PG8_STAGE(bufoff, gbase, voff) do { _Pragma("unroll") for (int _i = 0; _i < 2; ++_i) \
;         __builtin_amdgcn_global_load_lds((const unsigned*)((const char*)(gbase) + (voff)[_i]), (LAS unsigned*)(lds + (bufoff) + ldsw + _i * 8192), 16, 0, 0); } while (0)
; #define PG8_LDA(dst, b, h) do { _Pragma("unroll") for (int m = 0; m < 4; ++m) _Pragma("unroll") for (int k = 0; k < 2; ++k) dst[m][k] = *(const LAS bf16x8*)(lds + PG8_SA(b, h) + aoff + m * 2048 + k * 1024); } while (0)
; #define PG8_MMA(ai, bj, At, Bt) do { __builtin_amdgcn_s_setprio(1); _Pragma("unroll") for (int m = 0; m < 4; ++m) _Pragma("unroll") for (int n = 0; n < 2; ++n) _Pragma("unroll") for (int k = 0; k < 2; ++k) \
;         acc[ai][bj][m][n] = __builtin_amdgcn_mfma_f32_16x16x32_bf16(Bt[n][k], At[m][k], acc[ai][bj][m][n], 0, 0, 0); __builtin_amdgcn_s_setprio(0); } while (0)
; #define PG8_WAIT_V(n) asm volatile("s_waitcnt vmcnt(" #n ")" ::: "memory")
; #define PG8_WAIT_L(n) asm volatile("s_waitcnt lgkmcnt(" #n ")" ::: "memory")
; #define PG8_BAR __builtin_amdgcn_s_barrier()
; #define PG8_SCHED __builtin_amdgcn_sched_barrier(0)
; template <class Epi, class Sched>
; __device__ __forceinline__ void gemm_phase(LAS unsigned char* lds, const int K, const int lda, const int ldb, const Sched& S, const Epi& E) {
;     ...
;             PG8_LDA(At, 1, 1); PG8_STAGE(PG8_SB(1, 0), b3, voffB); PG8_STAGE(PG8_SB(1, 1), b3 + hB, voffB); PG8_STAGE(PG8_SA(1, 0), a3, voffA);
;             PG8_WAIT_V(8); PG8_WAIT_L(0); PG8_BAR; PG8_MMA(1, 0, At, B0); PG8_MMA(1, 1, At, B1); PG8_BAR; PG8_SCHED;
;         }
;         if (wr == 0) PG8_BAR;
	s_add_i32 s58, s60, s2
	v_lshl_add_u64 v[222:223], v[222:223], 0, s[26:27]
	s_mov_b32 m0, s58
	ds_read_b128 v[190:193], v145 offset:49152
	ds_read_b128 v[194:197], v248 offset:49152
	ds_read_b128 v[198:201], v145 offset:51200
	ds_read_b128 v[202:205], v248 offset:51200
	ds_read_b128 v[206:209], v145 offset:53248
	ds_read_b128 v[210:213], v248 offset:53248
	ds_read_b128 v[214:217], v145 offset:55296
	ds_read_b128 v[218:221], v248 offset:55296
	global_load_lds_dwordx4 v[222:223], off
	s_add_i32 m0, s58, 0x2000
	s_add_u32 s56, s56, 0x80080
	v_lshl_add_u64 v[222:223], v[224:225], 0, s[26:27]
	s_addc_u32 s57, s57, 0
	s_add_i32 s58, s61, s2
	global_load_lds_dwordx4 v[222:223], off
	v_lshl_add_u64 v[222:223], s[56:57], 0, v[130:131]
	s_mov_b32 m0, s58
	s_nop 0
	global_load_lds_dwordx4 v[222:223], off
	v_lshl_add_u64 v[222:223], s[56:57], 0, v[134:135]
	s_add_i32 m0, s58, 0x2000
	s_nop 0
	global_load_lds_dwordx4 v[222:223], off
	v_lshl_add_u64 v[222:223], v[226:227], 0, s[26:27]
	s_mov_b32 m0, s35
	s_nop 0
	global_load_lds_dwordx4 v[222:223], off
	v_lshl_add_u64 v[222:223], v[228:229], 0, s[26:27]
	s_mov_b32 m0, s38
	s_nop 0
	global_load_lds_dwordx4 v[222:223], off
	s_waitcnt vmcnt(8)
	s_waitcnt lgkmcnt(0)
	s_barrier
	s_setprio 1
	s_waitcnt lgkmcnt(0)
	v_mfma_f32_16x16x32_bf16 v[60:63], v[158:161], v[190:193], v[60:63]
	v_mfma_f32_16x16x32_bf16 v[52:55], v[166:169], v[190:193], v[52:55]
	v_mfma_f32_16x16x32_bf16 v[44:47], v[158:161], v[198:201], v[44:47]
	v_mfma_f32_16x16x32_bf16 v[36:39], v[166:169], v[198:201], v[36:39]
	v_mfma_f32_16x16x32_bf16 v[28:31], v[158:161], v[206:209], v[28:31]
	v_mfma_f32_16x16x32_bf16 v[20:23], v[166:169], v[206:209], v[20:23]
	v_mfma_f32_16x16x32_bf16 v[12:15], v[158:161], v[214:217], v[12:15]
	v_mfma_f32_16x16x32_bf16 v[4:7], v[166:169], v[214:217], v[4:7]
	v_mfma_f32_16x16x32_bf16 v[60:63], v[162:165], v[194:197], v[60:63]
	v_mfma_f32_16x16x32_bf16 v[52:55], v[170:173], v[194:197], v[52:55]
	v_mfma_f32_16x16x32_bf16 v[44:47], v[162:165], v[202:205], v[44:47]
	v_mfma_f32_16x16x32_bf16 v[36:39], v[170:173], v[202:205], v[36:39]
	v_mfma_f32_16x16x32_bf16 v[28:31], v[162:165], v[210:213], v[28:31]
	v_mfma_f32_16x16x32_bf16 v[20:23], v[170:173], v[210:213], v[20:23]
	v_mfma_f32_16x16x32_bf16 v[12:15], v[162:165], v[218:221], v[12:15]
	v_mfma_f32_16x16x32_bf16 v[4:7], v[170:173], v[218:221], v[4:7]
	s_setprio 0
	s_setprio 1
	v_mfma_f32_16x16x32_bf16 v[56:59], v[174:177], v[190:193], v[56:59]
	v_mfma_f32_16x16x32_bf16 v[48:51], v[182:185], v[190:193], v[48:51]
	v_mfma_f32_16x16x32_bf16 v[40:43], v[174:177], v[198:201], v[40:43]
	v_mfma_f32_16x16x32_bf16 v[32:35], v[182:185], v[198:201], v[32:35]
	v_mfma_f32_16x16x32_bf16 v[24:27], v[174:177], v[206:209], v[24:27]
	v_mfma_f32_16x16x32_bf16 v[16:19], v[182:185], v[206:209], v[16:19]
	v_mfma_f32_16x16x32_bf16 v[8:11], v[174:177], v[214:217], v[8:11]
	v_mfma_f32_16x16x32_bf16 v[0:3], v[182:185], v[214:217], v[0:3]
	v_mfma_f32_16x16x32_bf16 v[56:59], v[178:181], v[194:197], v[56:59]
	v_mfma_f32_16x16x32_bf16 v[48:51], v[186:189], v[194:197], v[48:51]
	v_mfma_f32_16x16x32_bf16 v[40:43], v[178:181], v[202:205], v[40:43]
	v_mfma_f32_16x16x32_bf16 v[32:35], v[186:189], v[202:205], v[32:35]
	v_mfma_f32_16x16x32_bf16 v[24:27], v[178:181], v[210:213], v[24:27]
	v_mfma_f32_16x16x32_bf16 v[16:19], v[186:189], v[210:213], v[16:19]
	v_mfma_f32_16x16x32_bf16 v[8:11], v[178:181], v[218:221], v[8:11]
	v_mfma_f32_16x16x32_bf16 v[0:3], v[186:189], v[218:221], v[0:3]
	s_setprio 0
	s_barrier
	s_add_i32 s55, s55, 2
	s_add_u32 s45, s45, 0x100
	s_addc_u32 s47, s47, 0
	s_add_u32 s52, s52, 0x100
	s_addc_u32 s53, s53, 0
	s_cmp_gt_u32 s55, 29
	s_cbranch_scc0 .LBB0_1448
	s_and_b64 vcc, exec, s[28:29]
	s_cbranch_vccz .LBB0_1451
	s_barrier
